# v20 = v19 + attention K/V LDS tiles double-buffered (one barrier per KV tile instead of two)
# speedup vs baseline: 1.0145x; 1.0001x over previous
.LBB0_703:
	s_or_b64 exec, exec, s[0:1]
	s_add_u32 s0, s8, 0x144d7900
	s_addc_u32 s1, s9, 0
	v_ashrrev_i32_e32 v9, 3, v4
	v_lshl_add_u32 v1, s50, 8, v1
	v_lshlrev_b32_e32 v122, 3, v5
	v_add_u32_e32 v5, v1, v9
	v_mov_b64_e32 v[28:29], s[0:1]
	v_lshlrev_b32_e32 v4, 4, v4
	v_ashrrev_i32_e32 v15, 3, v16
	global_load_dwordx4 v[232:235], v[26:27], off
	v_mad_i64_i32 v[26:27], s[24:25], v5, s71, 0
	v_mad_i64_i32 v[30:31], s[0:1], v5, s71, v[28:29]
	v_and_b32_e32 v4, 0x70, v4
	v_mov_b32_e32 v5, v117
	v_add_u32_e32 v1, v1, v15
	v_lshl_add_u64 v[30:31], v[30:31], 0, v[4:5]
	v_mad_i64_i32 v[28:29], s[0:1], v1, s71, v[28:29]
	v_lshl_add_u64 v[28:29], v[28:29], 0, v[4:5]
	global_load_dwordx4 v[236:239], v[30:31], off
	global_load_dwordx4 v[240:243], v[28:29], off
	v_and_b32_e32 v5, 64, v161
	v_mad_i64_i32 v[16:17], s[0:1], v1, s71, 0
	v_xor_b32_e32 v1, 32, v161
	v_add_u32_e32 v5, 64, v5
	v_cmp_lt_i32_e64 s[0:1], v1, v5
	s_mul_i32 s16, s50, 0x24000
	v_lshlrev_b32_e32 v25, 4, v8
	v_cndmask_b32_e64 v1, v161, v1, s[0:1]
	s_add_i32 s0, s51, 1
	v_or_b32_e32 v8, 32, v116
	s_mul_hi_i32 s1, s50, 0x24000
	s_add_u32 s24, s16, 0x14298900
	v_lshlrev_b32_e32 v123, 2, v1
	v_mul_u32_u24_e32 v163, 0x90, v116
	v_mul_u32_u24_e32 v1, 0xd0, v116
	v_mul_lo_u32 v35, v9, s72
	v_mul_u32_u24_e32 v116, 0x90, v8
	s_addc_u32 s25, s1, 0
	v_lshlrev_b64 v[8:9], 6, v[18:19]
	s_mul_i32 s16, s50, 0x120000
	v_lshl_add_u64 v[8:9], s[24:25], 0, v[8:9]
	s_mul_hi_i32 s1, s50, 0x120000
	s_add_u32 s26, s16, 0x1309f900
	v_lshl_add_u64 v[128:129], v[22:23], 1, v[8:9]
	s_addc_u32 s27, s1, 0
	v_lshlrev_b64 v[8:9], 9, v[18:19]
	v_lshlrev_b32_e32 v33, 4, v14
	v_mul_lo_u32 v36, v15, s72
	v_lshl_add_u64 v[8:9], s[26:27], 0, v[8:9]
	v_lshl_add_u64 v[14:15], v[20:21], 0, v[120:121]
	v_lshl_add_u64 v[130:131], v[14:15], 1, v[8:9]
	v_lshlrev_b64 v[8:9], 6, v[10:11]
	v_subrev_u32_e32 v30, 64, v12
	v_mov_b32_e32 v31, v117
	v_lshl_add_u64 v[8:9], s[24:25], 0, v[8:9]
	v_lshl_add_u64 v[132:133], v[30:31], 1, v[8:9]
	v_lshlrev_b64 v[8:9], 9, v[10:11]
	v_mul_lo_u32 v32, v10, s73
	v_lshl_add_u64 v[8:9], s[26:27], 0, v[8:9]
	v_lshl_add_u64 v[10:11], v[120:121], 0, v[12:13]
	v_mul_lo_u32 v5, v2, s73
	v_lshl_add_u64 v[134:135], v[10:11], 1, v[8:9]
	v_lshlrev_b64 v[8:9], 6, v[2:3]
	v_lshlrev_b64 v[2:3], 9, v[2:3]
	v_subrev_u32_e32 v28, 64, v6
	v_mov_b32_e32 v29, v117
	v_mul_lo_u32 v34, v18, s73
	v_lshlrev_b32_e32 v24, 4, v24
	v_or_b32_e32 v16, v16, v4
	v_or_b32_e32 v26, v26, v4
	v_lshl_add_u64 v[8:9], s[24:25], 0, v[8:9]
	v_lshl_add_u64 v[2:3], s[26:27], 0, v[2:3]
	v_lshl_add_u64 v[6:7], v[120:121], 0, v[6:7]
	v_mov_b32_e32 v104, 0
	v_sub_u32_e32 v162, v0, v122
	v_lshl_add_u64 v[124:125], v[16:17], 0, s[40:41]
	v_lshl_add_u64 v[126:127], v[26:27], 0, s[40:41]
	v_lshl_add_u64 v[136:137], v[28:29], 1, v[8:9]
	v_lshl_add_u64 v[138:139], v[6:7], 1, v[2:3]
	v_mov_b32_e32 v105, 0xf149f2ca
	v_add_u32_e32 v165, v5, v25
	v_add_u32_e32 v166, v32, v33
	v_add_u32_e32 v167, v34, v24
	v_add_u32_e32 v168, v4, v35
	v_add_u32_e32 v169, v4, v36
	v_add_u32_e32 v164, v0, v1
	v_mov_b32_e32 v0, 0
	v_mov_b32_e32 v1, v104
	v_mov_b32_e32 v2, v104
	v_mov_b32_e32 v3, v104
	v_mov_b32_e32 v4, v104
	v_mov_b32_e32 v5, v104
	v_mov_b32_e32 v6, v104
	v_mov_b32_e32 v7, v104
	v_mov_b32_e32 v8, v104
	v_mov_b32_e32 v9, v104
	v_mov_b32_e32 v10, v104
	v_mov_b32_e32 v11, v104
	v_mov_b32_e32 v12, v104
	v_mov_b32_e32 v13, v104
	v_mov_b32_e32 v14, v104
	v_mov_b32_e32 v15, v104
	v_mov_b32_e32 v16, 0
	v_mov_b32_e32 v17, v104
	v_mov_b32_e32 v18, v104
	v_mov_b32_e32 v19, v104
	v_mov_b32_e32 v20, v104
	v_mov_b32_e32 v21, v104
	v_mov_b32_e32 v22, v104
	v_mov_b32_e32 v23, v104
	v_mov_b32_e32 v24, v104
	v_mov_b32_e32 v25, v104
	v_mov_b32_e32 v26, v104
	v_mov_b32_e32 v27, v104
	v_mov_b32_e32 v28, v104
	v_mov_b32_e32 v29, v104
	v_mov_b32_e32 v30, v104
	v_mov_b32_e32 v31, v104
	s_waitcnt lgkmcnt(0)
	s_barrier
	v_mov_b32_e32 v253, 0x6000
	v_mov_b32_e32 v252, 0
.LBB0_704:
	s_waitcnt lgkmcnt(0)
	s_waitcnt vmcnt(0)
	ds_write_b128 v165, v[224:227]
	ds_write_b128 v166, v[228:231]
	ds_write_b128 v167, v[232:235]
	ds_write_b128 v168, v[236:239] offset:13312
	ds_write_b128 v169, v[240:243] offset:13312
	s_waitcnt lgkmcnt(0)
	s_barrier
	ds_read_b128 v[32:35], v164
	ds_read_b128 v[88:91], v164 offset:32
	v_lshl_add_u64 v[112:113], s[8:9], 0, v[138:139]
	v_lshl_add_u64 v[148:149], s[8:9], 0, v[136:137]
	v_lshl_add_u64 v[114:115], s[8:9], 0, v[134:135]
	v_lshl_add_u64 v[142:143], s[8:9], 0, v[132:133]
	v_lshl_add_u64 v[140:141], s[8:9], 0, v[130:131]
	v_lshl_add_u64 v[144:145], s[8:9], 0, v[128:129]
	v_lshl_add_u64 v[146:147], s[8:9], 0, v[126:127]
	v_cndmask_b32_e32 v113, v149, v113, vcc
	v_cndmask_b32_e32 v112, v148, v112, vcc
	v_cndmask_b32_e64 v115, v143, v115, s[4:5]
	v_cndmask_b32_e64 v114, v142, v114, s[4:5]
	v_lshl_add_u64 v[150:151], s[8:9], 0, v[124:125]
	v_cndmask_b32_e64 v145, v145, v141, s[6:7]
	v_cndmask_b32_e64 v144, v144, v140, s[6:7]
	global_load_dwordx4 v[236:239], v[146:147], off
	global_load_dwordx4 v[240:243], v[150:151], off
	global_load_dwordx4 v[224:227], v[112:113], off
	global_load_dwordx4 v[228:231], v[114:115], off
	global_load_dwordx4 v[232:235], v[144:145], off
	s_waitcnt lgkmcnt(1)
	v_mfma_f32_32x32x16_bf16 v[32:47], v[32:35], v[84:87], 0
	ds_read_b128 v[48:51], v164 offset:6656
	ds_read_b128 v[92:95], v164 offset:6688
	v_mov_b32_e32 v171, v105
	v_mov_b32_e32 v170, v104
	s_waitcnt lgkmcnt(1)
	v_mfma_f32_32x32x16_bf16 v[48:63], v[48:51], v[84:87], 0
	v_mfma_f32_32x32x16_bf16 v[32:47], v[88:91], v[80:83], v[32:47]
	ds_read_b128 v[88:91], v164 offset:64
	v_add_u32_e32 v172, v122, v163
	v_add_u32_e32 v143, 0x3000, v172
	v_add_u32_e32 v143, v252, v143
	v_add_u32_e32 v173, v122, v116
	s_waitcnt lgkmcnt(1)
	v_mfma_f32_32x32x16_bf16 v[48:63], v[92:95], v[80:83], v[48:63]
	ds_read_b128 v[100:103], v164 offset:96
	ds_read_b128 v[92:95], v164 offset:6720
	ds_read_b128 v[96:99], v164 offset:6752
	v_add_u32_e32 v174, v162, v163
	v_add_u32_e32 v175, v162, v116
	v_add_u32_e32 v142, 0x3000, v173
	v_add_u32_e32 v142, v252, v142
	v_add_u32_e32 v141, 0x3000, v174
	v_add_u32_e32 v141, v252, v141
	v_add_u32_e32 v140, 0x3000, v175
	v_add_u32_e32 v140, v252, v140
	s_waitcnt lgkmcnt(3)
	v_mfma_f32_32x32x16_bf16 v[32:47], v[88:91], v[76:79], v[32:47]
	s_add_i32 s0, s0, -1
	v_lshl_add_u64 v[124:125], v[124:125], 0, s[42:43]
	v_lshl_add_u64 v[126:127], v[126:127], 0, s[42:43]
	v_lshl_add_u64 v[128:129], v[128:129], 0, s[44:45]
	v_lshl_add_u64 v[130:131], v[130:131], 0, s[46:47]
	v_lshl_add_u64 v[132:133], v[132:133], 0, s[44:45]
	v_lshl_add_u64 v[134:135], v[134:135], 0, s[46:47]
	s_waitcnt lgkmcnt(1)
	v_mfma_f32_32x32x16_bf16 v[48:63], v[92:95], v[76:79], v[48:63]
	ds_read_b128 v[88:91], v164 offset:128
	ds_read_b128 v[104:107], v164 offset:160
	ds_read_b128 v[92:95], v164 offset:6784
	ds_read_b128 v[108:111], v164 offset:6816
	v_lshl_add_u64 v[136:137], v[136:137], 0, s[44:45]
	v_lshl_add_u64 v[138:139], v[138:139], 0, s[46:47]
	s_cmp_lg_u32 s0, 0
	v_mfma_f32_32x32x16_bf16 v[32:47], v[100:103], v[72:75], v[32:47]
	s_waitcnt lgkmcnt(4)
	v_mfma_f32_32x32x16_bf16 v[48:63], v[96:99], v[72:75], v[48:63]
	s_waitcnt lgkmcnt(0)
	v_mfma_f32_32x32x16_bf16 v[32:47], v[88:91], v[68:71], v[32:47]
	v_mfma_f32_32x32x16_bf16 v[48:63], v[92:95], v[68:71], v[48:63]
	s_nop 0
	ds_read2_b64 v[144:147], v143 offset0:128 offset1:130
	ds_read2_b64 v[148:151], v143 offset0:132 offset1:134
	ds_read2_b64 v[172:175], v142 offset0:128 offset1:130
	ds_read2_b64 v[176:179], v142 offset0:132 offset1:134
	ds_read2_b64 v[180:183], v143 offset0:136 offset1:138
	ds_read2_b64 v[184:187], v142 offset0:136 offset1:138
	ds_read2_b64 v[188:191], v141 offset0:140 offset1:142
	ds_read2_b64 v[192:195], v140 offset0:140 offset1:142
	v_mfma_f32_32x32x16_bf16 v[32:47], v[104:107], v[64:67], v[32:47]
	v_mfma_f32_32x32x16_bf16 v[48:63], v[108:111], v[64:67], v[48:63]
	s_nop 10
	v_max_f32_e32 v104, v33, v33
	v_max_f32_e32 v105, v32, v32
	v_max_f32_e32 v104, v105, v104
	v_max3_f32 v104, v104, v34, v35
	v_max3_f32 v104, v104, v36, v37
	v_max3_f32 v104, v104, v38, v39
	v_max3_f32 v104, v104, v40, v41
	v_max3_f32 v104, v104, v42, v43
	v_max3_f32 v104, v104, v44, v45
	v_max3_f32 v104, v104, v46, v47
	v_max3_f32 v104, v104, v48, v49
	v_max3_f32 v104, v104, v50, v51
	v_max3_f32 v104, v104, v52, v53
	v_max3_f32 v104, v104, v54, v55
	v_max3_f32 v104, v104, v56, v57
	v_max3_f32 v104, v104, v58, v59
	v_max3_f32 v104, v104, v60, v61
	v_max3_f32 v104, v104, v62, v63
	ds_bpermute_b32 v105, v123, v104
	s_waitcnt lgkmcnt(0)
	v_max3_f32 v105, v171, v104, v105
	v_sub_f32_e32 v104, v171, v105
	v_sub_f32_e32 v32, v32, v105
	v_sub_f32_e32 v33, v33, v105
	v_sub_f32_e32 v34, v34, v105
	v_sub_f32_e32 v35, v35, v105
	v_sub_f32_e32 v36, v36, v105
	v_sub_f32_e32 v37, v37, v105
	v_sub_f32_e32 v38, v38, v105
	v_sub_f32_e32 v39, v39, v105
	v_sub_f32_e32 v106, v42, v105
	v_exp_f32_e32 v42, v104
	v_exp_f32_e32 v32, v32
	v_exp_f32_e32 v33, v33
	s_nop 0
	v_cvt_pk_bf16_f32 v244, v32, v33
	v_exp_f32_e32 v104, v34
	v_exp_f32_e32 v107, v35
	v_exp_f32_e32 v108, v36
	v_exp_f32_e32 v109, v37
	v_exp_f32_e32 v110, v38
	v_exp_f32_e32 v111, v39
	v_sub_f32_e32 v43, v43, v105
	v_sub_f32_e32 v40, v40, v105
	v_sub_f32_e32 v41, v41, v105
	v_exp_f32_e32 v43, v43
	v_exp_f32_e32 v171, v40
	v_exp_f32_e32 v196, v41
	v_add_f32_e32 v34, 0, v32
	v_bfe_u32 v39, v32, 16, 1
	v_add_f32_e32 v222, v33, v34
	v_add3_u32 v32, v32, v39, s59
	v_lshrrev_b32_e32 v32, 16, v32
	v_sub_f32_e32 v44, v44, v105
	v_sub_f32_e32 v45, v45, v105
	v_sub_f32_e32 v46, v46, v105
	v_pk_mul_f32 v[30:31], v[30:31], v[42:43] op_sel_hi:[1,0]
	v_pk_mul_f32 v[28:29], v[28:29], v[42:43] op_sel_hi:[1,0]
	v_pk_mul_f32 v[26:27], v[26:27], v[42:43] op_sel_hi:[1,0]
	v_pk_mul_f32 v[24:25], v[24:25], v[42:43] op_sel_hi:[1,0]
	v_pk_mul_f32 v[22:23], v[22:23], v[42:43] op_sel_hi:[1,0]
	v_pk_mul_f32 v[20:21], v[20:21], v[42:43] op_sel_hi:[1,0]
	v_pk_mul_f32 v[18:19], v[18:19], v[42:43] op_sel_hi:[1,0]
	v_pk_mul_f32 v[16:17], v[16:17], v[42:43] op_sel_hi:[1,0]
	v_pk_mul_f32 v[14:15], v[14:15], v[42:43] op_sel_hi:[1,0]
	v_pk_mul_f32 v[12:13], v[12:13], v[42:43] op_sel_hi:[1,0]
	v_pk_mul_f32 v[10:11], v[10:11], v[42:43] op_sel_hi:[1,0]
	v_pk_mul_f32 v[8:9], v[8:9], v[42:43] op_sel_hi:[1,0]
	v_pk_mul_f32 v[6:7], v[6:7], v[42:43] op_sel_hi:[1,0]
	v_pk_mul_f32 v[4:5], v[4:5], v[42:43] op_sel_hi:[1,0]
	v_pk_mul_f32 v[2:3], v[2:3], v[42:43] op_sel_hi:[1,0]
	v_pk_mul_f32 v[0:1], v[0:1], v[42:43] op_sel_hi:[1,0]
	v_cvt_pk_bf16_f32 v35, v110, v111
	v_cvt_pk_bf16_f32 v34, v108, v109
	v_cvt_pk_bf16_f32 v33, v104, v107
	v_mov_b32_e32 v32, v244
	v_sub_f32_e32 v47, v47, v105
	v_exp_f32_e32 v106, v106
	v_exp_f32_e32 v44, v44
	v_exp_f32_e32 v45, v45
	v_exp_f32_e32 v46, v46
	v_mfma_f32_32x32x16_bf16 v[16:31], v[144:147], v[32:35], v[16:31]
	v_exp_f32_e32 v47, v47
	v_bfe_u32 v199, v45, 16, 1
	v_bfe_u32 v202, v171, 16, 1
	v_bfe_u32 v203, v106, 16, 1
	v_bfe_u32 v204, v44, 16, 1
	v_mfma_f32_32x32x16_bf16 v[0:15], v[172:175], v[32:35], v[0:15]
	v_bfe_u32 v205, v46, 16, 1
	v_bfe_u32 v198, v47, 16, 1
	v_add3_u32 v197, v45, v199, s59
	v_add3_u32 v199, v46, v205, s59
	v_add3_u32 v200, v44, v204, s59
	v_add3_u32 v201, v106, v203, s59
	v_add3_u32 v202, v171, v202, s59
	v_add3_u32 v198, v47, v198, s59
	v_add_f32_e32 v37, v104, v222
	v_lshrrev_b32_e32 v144, 16, v199
	v_cvt_pk_bf16_f32 v35, v46, v47
	v_cvt_pk_bf16_f32 v34, v44, v45
	v_cvt_pk_bf16_f32 v33, v106, v43
	v_cvt_pk_bf16_f32 v32, v171, v196
	v_add_f32_e32 v104, v107, v37
	v_sub_f32_e32 v48, v48, v105
	v_mfma_f32_32x32x16_bf16 v[16:31], v[148:151], v[32:35], v[16:31]
	v_sub_f32_e32 v49, v49, v105
	v_sub_f32_e32 v50, v50, v105
	v_sub_f32_e32 v51, v51, v105
	v_sub_f32_e32 v52, v52, v105
	v_sub_f32_e32 v53, v53, v105
	v_sub_f32_e32 v54, v54, v105
	v_sub_f32_e32 v55, v55, v105
	v_mfma_f32_32x32x16_bf16 v[0:15], v[176:179], v[32:35], v[0:15]
	v_add_f32_e32 v32, v108, v104
	v_add_f32_e32 v32, v109, v32
	v_add_f32_e32 v32, v110, v32
	v_add_f32_e32 v32, v111, v32
	v_add_f32_e32 v32, v171, v32
	v_sub_f32_e32 v56, v56, v105
	v_exp_f32_e32 v48, v48
	v_exp_f32_e32 v49, v49
	v_exp_f32_e32 v50, v50
	v_exp_f32_e32 v51, v51
	v_exp_f32_e32 v52, v52
	v_exp_f32_e32 v53, v53
	v_exp_f32_e32 v54, v54
	v_add_f32_e32 v32, v196, v32
	v_exp_f32_e32 v55, v55
	v_exp_f32_e32 v56, v56
	v_add_f32_e32 v32, v106, v32
	v_add_f32_e32 v32, v43, v32
	v_add_f32_e32 v32, v44, v32
	v_bfe_u32 v207, v53, 16, 1
	v_bfe_u32 v208, v51, 16, 1
	v_bfe_u32 v209, v49, 16, 1
	v_bfe_u32 v210, v48, 16, 1
	v_bfe_u32 v211, v50, 16, 1
	v_bfe_u32 v212, v52, 16, 1
	v_bfe_u32 v213, v54, 16, 1
	v_add_f32_e32 v32, v45, v32
	v_bfe_u32 v206, v55, 16, 1
	v_bfe_u32 v218, v56, 16, 1
	v_add3_u32 v203, v49, v209, s59
	v_add3_u32 v204, v51, v208, s59
	v_add3_u32 v205, v53, v207, s59
	v_add3_u32 v207, v54, v213, s59
	v_add3_u32 v208, v52, v212, s59
	v_add3_u32 v209, v50, v211, s59
	v_add3_u32 v210, v48, v210, s59
	v_add_f32_e32 v32, v46, v32
	v_add3_u32 v206, v55, v206, s59
	v_lshrrev_b32_e32 v145, 16, v210
	v_lshrrev_b32_e32 v146, 16, v209
	v_lshrrev_b32_e32 v147, 16, v208
	v_lshrrev_b32_e32 v172, 16, v207
	v_add_f32_e32 v32, v47, v32
	v_sub_f32_e32 v57, v57, v105
	v_sub_f32_e32 v58, v58, v105
	v_sub_f32_e32 v59, v59, v105
	v_sub_f32_e32 v60, v60, v105
	v_sub_f32_e32 v61, v61, v105
	v_sub_f32_e32 v62, v62, v105
	v_cvt_pk_bf16_f32 v37, v54, v55
	v_cvt_pk_bf16_f32 v36, v52, v53
	v_cvt_pk_bf16_f32 v35, v50, v51
	v_cvt_pk_bf16_f32 v34, v48, v49
	v_add_f32_e32 v32, v48, v32
	v_sub_f32_e32 v63, v63, v105
	v_exp_f32_e32 v57, v57
	v_exp_f32_e32 v58, v58
	v_exp_f32_e32 v59, v59
	v_exp_f32_e32 v60, v60
	v_exp_f32_e32 v61, v61
	v_exp_f32_e32 v62, v62
	v_mfma_f32_32x32x16_bf16 v[16:31], v[180:183], v[34:37], v[16:31]
	v_add_f32_e32 v32, v49, v32
	v_exp_f32_e32 v63, v63
	v_add_f32_e32 v32, v50, v32
	v_add_f32_e32 v32, v51, v32
	v_add_f32_e32 v32, v52, v32
	v_bfe_u32 v215, v61, 16, 1
	v_bfe_u32 v216, v59, 16, 1
	v_mfma_f32_32x32x16_bf16 v[0:15], v[184:187], v[34:37], v[0:15]
	v_bfe_u32 v217, v57, 16, 1
	v_bfe_u32 v219, v58, 16, 1
	v_bfe_u32 v220, v60, 16, 1
	v_bfe_u32 v221, v62, 16, 1
	v_add_f32_e32 v32, v53, v32
	v_bfe_u32 v214, v63, 16, 1
	v_add3_u32 v211, v57, v217, s59
	v_add3_u32 v212, v59, v216, s59
	v_add3_u32 v213, v61, v215, s59
	v_add3_u32 v215, v62, v221, s59
	v_add3_u32 v216, v60, v220, s59
	v_add3_u32 v217, v58, v219, s59
	v_add_f32_e32 v32, v54, v32
	v_add3_u32 v214, v63, v214, s59
	v_add_f32_e32 v32, v55, v32
	v_cvt_pk_bf16_f32 v41, v62, v63
	v_cvt_pk_bf16_f32 v40, v60, v61
	v_cvt_pk_bf16_f32 v39, v58, v59
	v_cvt_pk_bf16_f32 v38, v56, v57
	v_add_f32_e32 v32, v56, v32
	v_add_f32_e32 v32, v57, v32
	v_mfma_f32_32x32x16_bf16 v[16:31], v[188:191], v[38:41], v[16:31]
	v_add_f32_e32 v32, v58, v32
	v_add_f32_e32 v32, v59, v32
	v_add_f32_e32 v32, v60, v32
	v_add_f32_e32 v32, v61, v32
	v_add_f32_e32 v32, v62, v32
	v_add_f32_e32 v104, v63, v32
	v_fmac_f32_e32 v104, v170, v42
	v_mfma_f32_32x32x16_bf16 v[0:15], v[192:195], v[38:41], v[0:15]
	v_add_u32_e32 v164, v253, v164
	v_add_u32_e32 v165, v253, v165
	v_add_u32_e32 v166, v253, v166
	v_add_u32_e32 v167, v253, v167
	v_add_u32_e32 v168, v253, v168
	v_add_u32_e32 v169, v253, v169
	v_add_u32_e32 v140, v253, v140
	v_add_u32_e32 v141, v253, v141
	v_add_u32_e32 v142, v253, v142
	v_add_u32_e32 v143, v253, v143
	v_add_u32_e32 v252, v253, v252
	v_sub_u32_e32 v253, 0, v253
	s_cbranch_scc1 .LBB0_704
	s_waitcnt vmcnt(0)
	ds_write_b128 v165, v[224:227]
	ds_write_b128 v166, v[228:231]
	ds_write_b128 v167, v[232:235]
	ds_write_b128 v168, v[236:239] offset:13312
	ds_write_b128 v169, v[240:243] offset:13312
	s_waitcnt lgkmcnt(0)
	s_barrier
	ds_read_b128 v[32:35], v164
	ds_read_b128 v[36:39], v164 offset:32
	s_waitcnt lgkmcnt(1)
	v_mfma_f32_32x32x16_bf16 v[48:63], v[32:35], v[84:87], 0
	s_waitcnt lgkmcnt(0)
	v_mfma_f32_32x32x16_bf16 v[48:63], v[36:39], v[80:83], v[48:63]
	ds_read_b128 v[32:35], v164 offset:64
	ds_read_b128 v[36:39], v164 offset:96
	s_waitcnt lgkmcnt(1)
	v_mfma_f32_32x32x16_bf16 v[48:63], v[32:35], v[76:79], v[48:63]
	s_waitcnt lgkmcnt(0)
	v_mfma_f32_32x32x16_bf16 v[48:63], v[36:39], v[72:75], v[48:63]
	ds_read_b128 v[32:35], v164 offset:128
	ds_read_b128 v[36:39], v164 offset:160
	s_waitcnt lgkmcnt(1)
	v_mfma_f32_32x32x16_bf16 v[48:63], v[32:35], v[68:71], v[48:63]
	ds_read_b128 v[32:35], v164 offset:6656
	ds_read_b128 v[88:91], v164 offset:6688
	s_waitcnt lgkmcnt(2)
	v_mfma_f32_32x32x16_bf16 v[48:63], v[36:39], v[64:67], v[48:63]
	s_waitcnt lgkmcnt(1)
	v_mfma_f32_32x32x16_bf16 v[32:47], v[32:35], v[84:87], 0
	s_waitcnt lgkmcnt(0)
	v_mfma_f32_32x32x16_bf16 v[32:47], v[88:91], v[80:83], v[32:47]
	ds_read_b128 v[80:83], v164 offset:6720
	ds_read_b128 v[84:87], v164 offset:6752
	s_waitcnt lgkmcnt(1)
	v_mfma_f32_32x32x16_bf16 v[32:47], v[80:83], v[76:79], v[32:47]
	s_nop 3
	v_max_f32_e32 v80, v49, v49
	v_max_f32_e32 v81, v48, v48
	v_max_f32_e32 v80, v81, v80
	s_waitcnt lgkmcnt(0)
	v_mfma_f32_32x32x16_bf16 v[32:47], v[84:87], v[72:75], v[32:47]
	ds_read_b128 v[72:75], v164 offset:6784
	ds_read_b128 v[76:79], v164 offset:6816
	s_waitcnt lgkmcnt(1)
	v_mfma_f32_32x32x16_bf16 v[32:47], v[72:75], v[68:71], v[32:47]
	v_max3_f32 v68, v80, v50, v51
	v_max3_f32 v68, v68, v52, v53
	v_max3_f32 v68, v68, v54, v55
	v_max3_f32 v68, v68, v56, v57
	v_max3_f32 v68, v68, v58, v59
	v_max3_f32 v68, v68, v60, v61
	v_max3_f32 v68, v68, v62, v63
	s_waitcnt lgkmcnt(0)
	v_mfma_f32_32x32x16_bf16 v[32:47], v[76:79], v[64:67], v[32:47]
	s_nop 11
	v_max3_f32 v64, v68, v32, v33
	v_max3_f32 v64, v64, v34, v35
	v_max3_f32 v64, v64, v36, v37
	v_max3_f32 v64, v64, v38, v39
	v_max3_f32 v64, v64, v40, v41
	v_max3_f32 v64, v64, v42, v43
	v_max3_f32 v64, v64, v44, v45
	v_max3_f32 v64, v64, v46, v47
	ds_bpermute_b32 v65, v123, v64
	s_waitcnt lgkmcnt(0)
	v_max3_f32 v65, v105, v64, v65
	v_sub_f32_e32 v32, v32, v65
	v_exp_f32_e32 v66, v32
	v_sub_f32_e32 v32, v33, v65
	v_exp_f32_e32 v67, v32
	v_sub_f32_e32 v32, v34, v65
	v_exp_f32_e32 v68, v32
	v_sub_f32_e32 v32, v35, v65
	v_exp_f32_e32 v69, v32
	v_sub_f32_e32 v32, v36, v65
	v_exp_f32_e32 v70, v32
	v_sub_f32_e32 v32, v37, v65
	v_exp_f32_e32 v71, v32
	v_sub_f32_e32 v32, v38, v65
	v_exp_f32_e32 v72, v32
	v_sub_f32_e32 v32, v39, v65
	v_exp_f32_e32 v73, v32
	v_sub_f32_e32 v32, v40, v65
	v_exp_f32_e32 v74, v32
	v_sub_f32_e32 v32, v41, v65
	v_exp_f32_e32 v75, v32
	v_sub_f32_e32 v32, v42, v65
	v_sub_f32_e32 v48, v48, v65
	v_exp_f32_e32 v76, v32
	v_sub_f32_e32 v32, v43, v65
	v_exp_f32_e32 v48, v48
	v_sub_f32_e32 v49, v49, v65
	v_exp_f32_e32 v77, v32
	v_sub_f32_e32 v32, v44, v65
	v_exp_f32_e32 v49, v49
	v_sub_f32_e32 v50, v50, v65
	v_sub_f32_e32 v55, v55, v65
	v_exp_f32_e32 v78, v32
	v_sub_f32_e32 v32, v45, v65
	v_exp_f32_e32 v50, v50
	v_sub_f32_e32 v51, v51, v65
	v_sub_f32_e32 v53, v53, v65
	v_exp_f32_e32 v55, v55
	v_exp_f32_e32 v79, v32
	v_sub_f32_e32 v32, v46, v65
	v_exp_f32_e32 v51, v51
	v_sub_f32_e32 v52, v52, v65
	v_exp_f32_e32 v53, v53
	v_sub_f32_e32 v54, v54, v65
	v_exp_f32_e32 v80, v32
	v_sub_f32_e32 v32, v47, v65
	v_sub_f32_e32 v64, v105, v65
	v_exp_f32_e32 v52, v52
	v_exp_f32_e32 v54, v54
	v_sub_f32_e32 v56, v56, v65
	v_sub_f32_e32 v57, v57, v65
	v_sub_f32_e32 v58, v58, v65
	v_sub_f32_e32 v59, v59, v65
	v_sub_f32_e32 v60, v60, v65
	v_sub_f32_e32 v61, v61, v65
	v_sub_f32_e32 v62, v62, v65
	v_sub_f32_e32 v63, v63, v65
	v_exp_f32_e32 v65, v32
	v_add_f32_e32 v32, 0, v48
	v_add_f32_e32 v32, v49, v32
	v_add_f32_e32 v44, v50, v32
	ds_read2_b64 v[32:35], v143 offset0:128 offset1:130
	v_exp_f32_e32 v64, v64
	v_cvt_pk_bf16_f32 v39, v54, v55
	v_cvt_pk_bf16_f32 v38, v52, v53
	v_cvt_pk_bf16_f32 v37, v50, v51
	v_cvt_pk_bf16_f32 v36, v48, v49
	ds_read2_b64 v[40:43], v142 offset0:128 offset1:130
	v_pk_mul_f32 v[30:31], v[30:31], v[64:65] op_sel_hi:[1,0]
	v_pk_mul_f32 v[28:29], v[28:29], v[64:65] op_sel_hi:[1,0]
	v_pk_mul_f32 v[26:27], v[26:27], v[64:65] op_sel_hi:[1,0]
	v_pk_mul_f32 v[24:25], v[24:25], v[64:65] op_sel_hi:[1,0]
	v_pk_mul_f32 v[22:23], v[22:23], v[64:65] op_sel_hi:[1,0]
	v_pk_mul_f32 v[20:21], v[20:21], v[64:65] op_sel_hi:[1,0]
	v_pk_mul_f32 v[18:19], v[18:19], v[64:65] op_sel_hi:[1,0]
	v_pk_mul_f32 v[16:17], v[16:17], v[64:65] op_sel_hi:[1,0]
	v_exp_f32_e32 v57, v57
	v_exp_f32_e32 v59, v59
	s_waitcnt lgkmcnt(1)
	v_mfma_f32_32x32x16_bf16 v[16:31], v[32:35], v[36:39], v[16:31]
	v_add_f32_e32 v32, v51, v44
	v_exp_f32_e32 v56, v56
	v_exp_f32_e32 v58, v58
	v_exp_f32_e32 v60, v60
	v_exp_f32_e32 v62, v62
	v_add_f32_e32 v32, v52, v32
	v_exp_f32_e32 v61, v61
	v_exp_f32_e32 v63, v63
	v_add_f32_e32 v32, v53, v32
	v_pk_mul_f32 v[14:15], v[14:15], v[64:65] op_sel_hi:[1,0]
	v_pk_mul_f32 v[12:13], v[12:13], v[64:65] op_sel_hi:[1,0]
	v_pk_mul_f32 v[10:11], v[10:11], v[64:65] op_sel_hi:[1,0]
	v_pk_mul_f32 v[8:9], v[8:9], v[64:65] op_sel_hi:[1,0]
	v_pk_mul_f32 v[6:7], v[6:7], v[64:65] op_sel_hi:[1,0]
	v_pk_mul_f32 v[4:5], v[4:5], v[64:65] op_sel_hi:[1,0]
	v_pk_mul_f32 v[2:3], v[2:3], v[64:65] op_sel_hi:[1,0]
	v_pk_mul_f32 v[0:1], v[0:1], v[64:65] op_sel_hi:[1,0]
	v_add_f32_e32 v32, v54, v32
	v_add_f32_e32 v48, v55, v32
	s_waitcnt lgkmcnt(0)
	v_mfma_f32_32x32x16_bf16 v[0:15], v[40:43], v[36:39], v[0:15]
	ds_read2_b64 v[32:35], v143 offset0:132 offset1:134
	ds_read2_b64 v[44:47], v142 offset0:132 offset1:134
	v_add_f32_e32 v40, v56, v48
	v_bfe_u32 v38, v56, 16, 1
	v_bfe_u32 v39, v58, 16, 1
	v_bfe_u32 v48, v62, 16, 1
	v_add3_u32 v48, v62, v48, s59
	v_add3_u32 v39, v58, v39, s59
	v_add3_u32 v38, v56, v38, s59
	v_lshrrev_b32_e32 v49, 16, v38
	v_lshrrev_b32_e32 v50, 16, v39
	v_cvt_pk_bf16_f32 v39, v62, v63
	v_cvt_pk_bf16_f32 v38, v60, v61
	v_cvt_pk_bf16_f32 v37, v58, v59
	v_cvt_pk_bf16_f32 v36, v56, v57
	s_waitcnt lgkmcnt(1)
	s_nop 0
	v_mfma_f32_32x32x16_bf16 v[16:31], v[32:35], v[36:39], v[16:31]
	v_add_f32_e32 v32, v57, v40
	v_add_f32_e32 v32, v58, v32
	v_add_f32_e32 v32, v59, v32
	v_add_f32_e32 v32, v60, v32
	v_add_f32_e32 v32, v61, v32
	v_add_f32_e32 v32, v62, v32
	v_add_f32_e32 v32, v63, v32
	s_waitcnt lgkmcnt(0)
	v_mfma_f32_32x32x16_bf16 v[0:15], v[44:47], v[36:39], v[0:15]
	v_add_f32_e32 v44, v66, v32
	ds_read2_b64 v[32:35], v143 offset0:136 offset1:138
	v_cvt_pk_bf16_f32 v39, v72, v73
	v_cvt_pk_bf16_f32 v38, v70, v71
	v_cvt_pk_bf16_f32 v37, v68, v69
	v_cvt_pk_bf16_f32 v36, v66, v67
	ds_read2_b64 v[40:43], v142 offset0:136 offset1:138
	s_waitcnt lgkmcnt(1)
	v_mfma_f32_32x32x16_bf16 v[16:31], v[32:35], v[36:39], v[16:31]
	v_add_f32_e32 v32, v67, v44
	v_add_f32_e32 v32, v68, v32
	v_add_f32_e32 v32, v69, v32
	v_add_f32_e32 v32, v70, v32
	v_add_f32_e32 v32, v71, v32
	v_add_f32_e32 v32, v72, v32
	v_add_f32_e32 v32, v73, v32
	v_add_f32_e32 v32, v74, v32
	v_add_f32_e32 v32, v75, v32
	v_add_f32_e32 v32, v76, v32
	v_add_f32_e32 v32, v77, v32
	v_add_f32_e32 v32, v78, v32
	v_add_f32_e32 v32, v79, v32
	v_add_f32_e32 v32, v80, v32
	s_waitcnt lgkmcnt(0)
	v_mfma_f32_32x32x16_bf16 v[0:15], v[40:43], v[36:39], v[0:15]
	v_add_f32_e32 v40, v65, v32
	v_bfe_u32 v32, v74, 16, 1
	v_bfe_u32 v33, v76, 16, 1
	v_add3_u32 v33, v76, v33, s59
	v_add3_u32 v32, v74, v32, s59
	v_lshrrev_b32_e32 v43, 16, v32
	v_lshrrev_b32_e32 v44, 16, v33
	ds_read2_b64 v[32:35], v141 offset0:140 offset1:142
	v_fmac_f32_e32 v40, v104, v64
	v_cvt_pk_bf16_f32 v39, v80, v65
	ds_bpermute_b32 v41, v123, v40
	v_cvt_pk_bf16_f32 v38, v78, v79
	v_cvt_pk_bf16_f32 v37, v76, v77
	v_cvt_pk_bf16_f32 v36, v74, v75
	v_mov_b32_e32 v123, v117
	s_waitcnt lgkmcnt(0)
	v_add_f32_e32 v40, v40, v41
	v_mfma_f32_32x32x16_bf16 v[16:31], v[32:35], v[36:39], v[16:31]
	ds_read2_b64 v[32:35], v140 offset0:140 offset1:142
	v_div_scale_f32 v41, s[0:1], v40, v40, 1.0
	v_rcp_f32_e32 v42, v41
	s_waitcnt lgkmcnt(0)
	v_mfma_f32_32x32x16_bf16 v[0:15], v[32:35], v[36:39], v[0:15]
	v_fma_f32 v32, -v41, v42, 1.0
	v_fmac_f32_e32 v42, v32, v42
	v_div_scale_f32 v32, vcc, 1.0, v40, 1.0
	v_mul_f32_e32 v33, v32, v42
	v_fma_f32 v34, -v41, v33, v32
	v_fmac_f32_e32 v33, v34, v42
	v_fma_f32 v32, -v41, v33, v32
	v_div_fmas_f32 v32, v32, v42, v33
	v_div_fixup_f32 v32, v32, v40, 1.0
	v_mov_b32_e32 v38, v16
	v_mov_b32_e32 v39, v18
	v_mov_b32_e32 v18, v17
	v_lshlrev_b64 v[34:35], 11, v[118:119]
	v_pk_mul_f32 v[38:39], v[38:39], v[32:33] op_sel_hi:[1,0]
	v_pk_mul_f32 v[16:17], v[18:19], v[32:33] op_sel_hi:[1,0]
	v_lshl_add_u64 v[34:35], s[8:9], 0, v[34:35]
	v_and_b32_sdwa v19, v38, v159 dst_sel:DWORD dst_unused:UNUSED_PAD src0_sel:WORD_1 src1_sel:DWORD
	v_and_b32_sdwa v33, v17, v159 dst_sel:DWORD dst_unused:UNUSED_PAD src0_sel:WORD_1 src1_sel:DWORD
	v_lshl_add_u64 v[34:35], v[120:121], 1, v[34:35]
	v_and_b32_sdwa v18, v39, v159 dst_sel:DWORD dst_unused:UNUSED_PAD src0_sel:WORD_1 src1_sel:DWORD
	v_add3_u32 v19, v38, v19, s59
	v_and_b32_sdwa v38, v16, v159 dst_sel:DWORD dst_unused:UNUSED_PAD src0_sel:WORD_1 src1_sel:DWORD
	v_add3_u32 v17, v17, v33, s59
	v_lshl_add_u64 v[34:35], v[34:35], 0, v[122:123]
	v_add3_u32 v18, v39, v18, s59
	v_add3_u32 v16, v16, v38, s59
	v_and_b32_e32 v17, 0xffff0000, v17
	v_and_b32_e32 v16, 0xffff0000, v16
	v_or_b32_sdwa v17, v17, v18 dst_sel:DWORD dst_unused:UNUSED_PAD src0_sel:DWORD src1_sel:WORD_1
	v_add_co_u32_e32 v18, vcc, s61, v34
	v_or_b32_sdwa v16, v16, v19 dst_sel:DWORD dst_unused:UNUSED_PAD src0_sel:DWORD src1_sel:WORD_1
	s_nop 0
	v_addc_co_u32_e32 v19, vcc, 0, v35, vcc
	global_store_dwordx2 v[18:19], v[16:17], off offset:3840
	v_mov_b32_e32 v16, v20
	v_mov_b32_e32 v17, v22
	v_pk_mul_f32 v[16:17], v[16:17], v[32:33] op_sel_hi:[1,0]
	v_mov_b32_e32 v22, v21
	v_pk_mul_f32 v[18:19], v[22:23], v[32:33] op_sel_hi:[1,0]
	v_and_b32_sdwa v20, v17, v159 dst_sel:DWORD dst_unused:UNUSED_PAD src0_sel:WORD_1 src1_sel:DWORD
	v_and_b32_sdwa v21, v16, v159 dst_sel:DWORD dst_unused:UNUSED_PAD src0_sel:WORD_1 src1_sel:DWORD
	v_add3_u32 v16, v16, v21, s59
	v_add3_u32 v17, v17, v20, s59
	v_and_b32_sdwa v20, v19, v159 dst_sel:DWORD dst_unused:UNUSED_PAD src0_sel:WORD_1 src1_sel:DWORD
	v_and_b32_sdwa v21, v18, v159 dst_sel:DWORD dst_unused:UNUSED_PAD src0_sel:WORD_1 src1_sel:DWORD
	v_add3_u32 v19, v19, v20, s59
	v_add3_u32 v18, v18, v21, s59
	v_and_b32_e32 v19, 0xffff0000, v19
	v_and_b32_e32 v18, 0xffff0000, v18
	v_lshl_add_u64 v[36:37], v[34:35], 0, s[48:49]
	v_or_b32_sdwa v17, v19, v17 dst_sel:DWORD dst_unused:UNUSED_PAD src0_sel:DWORD src1_sel:WORD_1
	v_or_b32_sdwa v16, v18, v16 dst_sel:DWORD dst_unused:UNUSED_PAD src0_sel:DWORD src1_sel:WORD_1
	global_store_dwordx2 v[36:37], v[16:17], off offset:16
	v_mov_b32_e32 v16, v24
	v_mov_b32_e32 v17, v26
	v_pk_mul_f32 v[16:17], v[16:17], v[32:33] op_sel_hi:[1,0]
	v_mov_b32_e32 v26, v25
	v_pk_mul_f32 v[18:19], v[26:27], v[32:33] op_sel_hi:[1,0]
	v_and_b32_sdwa v20, v17, v159 dst_sel:DWORD dst_unused:UNUSED_PAD src0_sel:WORD_1 src1_sel:DWORD
	v_and_b32_sdwa v21, v16, v159 dst_sel:DWORD dst_unused:UNUSED_PAD src0_sel:WORD_1 src1_sel:DWORD
	v_add3_u32 v16, v16, v21, s59
	v_add3_u32 v17, v17, v20, s59
	v_and_b32_sdwa v20, v19, v159 dst_sel:DWORD dst_unused:UNUSED_PAD src0_sel:WORD_1 src1_sel:DWORD
	v_and_b32_sdwa v21, v18, v159 dst_sel:DWORD dst_unused:UNUSED_PAD src0_sel:WORD_1 src1_sel:DWORD
	v_add3_u32 v19, v19, v20, s59
	v_add3_u32 v18, v18, v21, s59
	v_and_b32_e32 v19, 0xffff0000, v19
	v_and_b32_e32 v18, 0xffff0000, v18
	v_or_b32_sdwa v17, v19, v17 dst_sel:DWORD dst_unused:UNUSED_PAD src0_sel:DWORD src1_sel:WORD_1
	v_or_b32_sdwa v16, v18, v16 dst_sel:DWORD dst_unused:UNUSED_PAD src0_sel:DWORD src1_sel:WORD_1
	global_store_dwordx2 v[36:37], v[16:17], off offset:32
	v_mov_b32_e32 v16, v28
	v_mov_b32_e32 v17, v30
	v_pk_mul_f32 v[16:17], v[16:17], v[32:33] op_sel_hi:[1,0]
	v_mov_b32_e32 v30, v29
	v_pk_mul_f32 v[18:19], v[30:31], v[32:33] op_sel_hi:[1,0]
	v_and_b32_sdwa v20, v17, v159 dst_sel:DWORD dst_unused:UNUSED_PAD src0_sel:WORD_1 src1_sel:DWORD
	v_and_b32_sdwa v21, v16, v159 dst_sel:DWORD dst_unused:UNUSED_PAD src0_sel:WORD_1 src1_sel:DWORD
	v_add3_u32 v16, v16, v21, s59
	v_add3_u32 v17, v17, v20, s59
	v_and_b32_sdwa v20, v19, v159 dst_sel:DWORD dst_unused:UNUSED_PAD src0_sel:WORD_1 src1_sel:DWORD
	v_and_b32_sdwa v21, v18, v159 dst_sel:DWORD dst_unused:UNUSED_PAD src0_sel:WORD_1 src1_sel:DWORD
	v_add3_u32 v19, v19, v20, s59
	v_add3_u32 v18, v18, v21, s59
	v_and_b32_e32 v19, 0xffff0000, v19
	v_and_b32_e32 v18, 0xffff0000, v18
	v_or_b32_sdwa v17, v19, v17 dst_sel:DWORD dst_unused:UNUSED_PAD src0_sel:DWORD src1_sel:WORD_1
	v_or_b32_sdwa v16, v18, v16 dst_sel:DWORD dst_unused:UNUSED_PAD src0_sel:DWORD src1_sel:WORD_1
	global_store_dwordx2 v[36:37], v[16:17], off offset:48
	v_mov_b32_e32 v16, v0
	v_mov_b32_e32 v17, v2
	v_pk_mul_f32 v[16:17], v[16:17], v[32:33] op_sel_hi:[1,0]
	v_mov_b32_e32 v2, v1
	v_pk_mul_f32 v[0:1], v[2:3], v[32:33] op_sel_hi:[1,0]
	v_and_b32_sdwa v2, v17, v159 dst_sel:DWORD dst_unused:UNUSED_PAD src0_sel:WORD_1 src1_sel:DWORD
	v_and_b32_sdwa v3, v16, v159 dst_sel:DWORD dst_unused:UNUSED_PAD src0_sel:WORD_1 src1_sel:DWORD
	v_add3_u32 v3, v16, v3, s59
	v_add3_u32 v2, v17, v2, s59
	v_and_b32_sdwa v16, v1, v159 dst_sel:DWORD dst_unused:UNUSED_PAD src0_sel:WORD_1 src1_sel:DWORD
	v_and_b32_sdwa v17, v0, v159 dst_sel:DWORD dst_unused:UNUSED_PAD src0_sel:WORD_1 src1_sel:DWORD
	v_add3_u32 v1, v1, v16, s59
	v_add3_u32 v0, v0, v17, s59
	v_and_b32_e32 v1, 0xffff0000, v1
	v_and_b32_e32 v0, 0xffff0000, v0
	v_or_b32_sdwa v1, v1, v2 dst_sel:DWORD dst_unused:UNUSED_PAD src0_sel:DWORD src1_sel:WORD_1
	v_or_b32_sdwa v0, v0, v3 dst_sel:DWORD dst_unused:UNUSED_PAD src0_sel:DWORD src1_sel:WORD_1
	global_store_dwordx2 v[36:37], v[0:1], off offset:64
	v_mov_b32_e32 v0, v4
	v_mov_b32_e32 v1, v6
	v_pk_mul_f32 v[0:1], v[0:1], v[32:33] op_sel_hi:[1,0]
	v_mov_b32_e32 v6, v5
	v_pk_mul_f32 v[2:3], v[6:7], v[32:33] op_sel_hi:[1,0]
	v_and_b32_sdwa v4, v1, v159 dst_sel:DWORD dst_unused:UNUSED_PAD src0_sel:WORD_1 src1_sel:DWORD
	v_and_b32_sdwa v5, v0, v159 dst_sel:DWORD dst_unused:UNUSED_PAD src0_sel:WORD_1 src1_sel:DWORD
	v_add3_u32 v0, v0, v5, s59
	v_add3_u32 v1, v1, v4, s59
	v_and_b32_sdwa v4, v3, v159 dst_sel:DWORD dst_unused:UNUSED_PAD src0_sel:WORD_1 src1_sel:DWORD
	v_and_b32_sdwa v5, v2, v159 dst_sel:DWORD dst_unused:UNUSED_PAD src0_sel:WORD_1 src1_sel:DWORD
	v_add3_u32 v3, v3, v4, s59
	v_add3_u32 v2, v2, v5, s59
	v_and_b32_e32 v3, 0xffff0000, v3
	v_and_b32_e32 v2, 0xffff0000, v2
	v_or_b32_sdwa v1, v3, v1 dst_sel:DWORD dst_unused:UNUSED_PAD src0_sel:DWORD src1_sel:WORD_1
	v_or_b32_sdwa v0, v2, v0 dst_sel:DWORD dst_unused:UNUSED_PAD src0_sel:DWORD src1_sel:WORD_1
	global_store_dwordx2 v[36:37], v[0:1], off offset:80
	v_mov_b32_e32 v0, v8
	v_mov_b32_e32 v1, v10
	v_pk_mul_f32 v[0:1], v[0:1], v[32:33] op_sel_hi:[1,0]
	v_mov_b32_e32 v10, v9
	v_pk_mul_f32 v[2:3], v[10:11], v[32:33] op_sel_hi:[1,0]
	v_and_b32_sdwa v4, v1, v159 dst_sel:DWORD dst_unused:UNUSED_PAD src0_sel:WORD_1 src1_sel:DWORD
	v_and_b32_sdwa v5, v0, v159 dst_sel:DWORD dst_unused:UNUSED_PAD src0_sel:WORD_1 src1_sel:DWORD
	v_add3_u32 v0, v0, v5, s59
	v_add3_u32 v1, v1, v4, s59
	v_and_b32_sdwa v4, v3, v159 dst_sel:DWORD dst_unused:UNUSED_PAD src0_sel:WORD_1 src1_sel:DWORD
	v_and_b32_sdwa v5, v2, v159 dst_sel:DWORD dst_unused:UNUSED_PAD src0_sel:WORD_1 src1_sel:DWORD
	v_add3_u32 v3, v3, v4, s59
	v_add3_u32 v2, v2, v5, s59
	v_and_b32_e32 v3, 0xffff0000, v3
	v_and_b32_e32 v2, 0xffff0000, v2
	v_or_b32_sdwa v1, v3, v1 dst_sel:DWORD dst_unused:UNUSED_PAD src0_sel:DWORD src1_sel:WORD_1
	v_or_b32_sdwa v0, v2, v0 dst_sel:DWORD dst_unused:UNUSED_PAD src0_sel:DWORD src1_sel:WORD_1
	global_store_dwordx2 v[36:37], v[0:1], off offset:96
	v_mov_b32_e32 v0, v12
	v_mov_b32_e32 v1, v14
	v_pk_mul_f32 v[0:1], v[0:1], v[32:33] op_sel_hi:[1,0]
	v_mov_b32_e32 v14, v13
	v_pk_mul_f32 v[2:3], v[14:15], v[32:33] op_sel_hi:[1,0]
	v_and_b32_sdwa v4, v1, v159 dst_sel:DWORD dst_unused:UNUSED_PAD src0_sel:WORD_1 src1_sel:DWORD
	v_and_b32_sdwa v5, v0, v159 dst_sel:DWORD dst_unused:UNUSED_PAD src0_sel:WORD_1 src1_sel:DWORD
	v_add3_u32 v0, v0, v5, s59
	v_add3_u32 v1, v1, v4, s59
	v_and_b32_sdwa v4, v3, v159 dst_sel:DWORD dst_unused:UNUSED_PAD src0_sel:WORD_1 src1_sel:DWORD
	v_and_b32_sdwa v5, v2, v159 dst_sel:DWORD dst_unused:UNUSED_PAD src0_sel:WORD_1 src1_sel:DWORD
	v_add3_u32 v3, v3, v4, s59
	v_add3_u32 v2, v2, v5, s59
	v_and_b32_e32 v3, 0xffff0000, v3
	v_and_b32_e32 v2, 0xffff0000, v2
	v_or_b32_sdwa v1, v3, v1 dst_sel:DWORD dst_unused:UNUSED_PAD src0_sel:DWORD src1_sel:WORD_1
	v_or_b32_sdwa v0, v2, v0 dst_sel:DWORD dst_unused:UNUSED_PAD src0_sel:DWORD src1_sel:WORD_1
	global_store_dwordx2 v[36:37], v[0:1], off offset:112
	s_branch .LBB0_579

.LBB0_1683:
	s_or_b64 exec, exec, s[0:1]
	s_add_u32 s0, s8, 0x144d7900
	s_addc_u32 s1, s9, 0
	v_ashrrev_i32_e32 v13, 3, v2
	v_lshl_add_u32 v7, s52, 8, v7
	v_lshlrev_b32_e32 v2, 4, v2
	v_lshlrev_b32_e32 v122, 3, v15
	v_add_u32_e32 v15, v7, v13
	v_mov_b64_e32 v[26:27], s[0:1]
	v_and_b32_e32 v30, 0x70, v2
	v_ashrrev_i32_e32 v2, 3, v14
	v_mad_i64_i32 v[28:29], s[0:1], v15, s73, v[26:27]
	v_mov_b32_e32 v31, v117
	v_add_u32_e32 v7, v7, v2
	v_lshl_add_u64 v[28:29], v[28:29], 0, v[30:31]
	v_mad_i64_i32 v[26:27], s[0:1], v7, s73, v[26:27]
	global_load_dwordx4 v[232:235], v[24:25], off
	v_lshl_add_u64 v[26:27], v[26:27], 0, v[30:31]
	global_load_dwordx4 v[236:239], v[28:29], off
	global_load_dwordx4 v[240:243], v[26:27], off
	v_and_b32_e32 v23, 64, v157
	v_mad_i64_i32 v[24:25], s[24:25], v15, s73, 0
	v_mad_i64_i32 v[14:15], s[0:1], v7, s73, 0
	v_xor_b32_e32 v7, 32, v157
	v_add_u32_e32 v23, 64, v23
	v_cmp_lt_i32_e64 s[0:1], v7, v23
	v_mul_lo_u32 v35, v2, s75
	v_or_b32_e32 v2, 32, v3
	v_cndmask_b32_e64 v7, v157, v7, s[0:1]
	s_mul_i32 s0, s52, 0x24000
	s_mul_hi_i32 s1, s52, 0x24000
	s_add_u32 s0, s0, 0x14298900
	v_mul_u32_u24_e32 v159, 0x90, v3
	v_mul_u32_u24_e32 v23, 0xd0, v3
	v_mul_u32_u24_e32 v160, 0x90, v2
	s_addc_u32 s1, s1, 0
	v_lshlrev_b64 v[2:3], 6, v[16:17]
	s_mul_hi_i32 s16, s52, 0x120000
	s_mul_i32 s52, s52, 0x120000
	v_lshl_add_u64 v[2:3], s[0:1], 0, v[2:3]
	s_add_u32 s24, s52, 0x1309f900
	v_lshl_add_u64 v[128:129], v[20:21], 1, v[2:3]
	s_addc_u32 s25, s16, 0
	v_lshlrev_b64 v[2:3], 9, v[16:17]
	v_lshlrev_b32_e32 v123, 2, v7
	v_lshlrev_b32_e32 v32, 4, v6
	v_lshl_add_u64 v[2:3], s[24:25], 0, v[2:3]
	v_lshl_add_u64 v[6:7], v[18:19], 0, v[120:121]
	v_lshl_add_u64 v[130:131], v[6:7], 1, v[2:3]
	v_lshlrev_b64 v[2:3], 6, v[8:9]
	v_subrev_u32_e32 v28, 64, v10
	v_mov_b32_e32 v29, v117
	v_lshl_add_u64 v[2:3], s[0:1], 0, v[2:3]
	v_lshl_add_u64 v[132:133], v[28:29], 1, v[2:3]
	v_lshlrev_b64 v[2:3], 9, v[8:9]
	v_lshl_add_u64 v[2:3], s[24:25], 0, v[2:3]
	v_lshl_add_u64 v[6:7], v[120:121], 0, v[10:11]
	v_lshl_add_u64 v[134:135], v[6:7], 1, v[2:3]
	v_lshlrev_b64 v[2:3], 6, v[0:1]
	v_subrev_u32_e32 v26, 64, v4
	v_mov_b32_e32 v27, v117
	v_mul_lo_u32 v31, v0, s76
	v_lshl_add_u64 v[2:3], s[0:1], 0, v[2:3]
	v_lshlrev_b64 v[0:1], 9, v[0:1]
	v_mul_lo_u32 v33, v8, s76
	v_lshlrev_b32_e32 v12, 4, v12
	v_mul_lo_u32 v34, v16, s76
	v_lshlrev_b32_e32 v22, 4, v22
	v_mul_lo_u32 v13, v13, s75
	v_or_b32_e32 v14, v14, v30
	v_or_b32_e32 v24, v24, v30
	v_lshl_add_u64 v[136:137], v[26:27], 1, v[2:3]
	v_lshl_add_u64 v[0:1], s[24:25], 0, v[0:1]
	v_lshl_add_u64 v[2:3], v[120:121], 0, v[4:5]
	v_mov_b32_e32 v108, 0
	v_sub_u32_e32 v158, v116, v122
	v_lshl_add_u64 v[124:125], v[14:15], 0, s[42:43]
	v_lshl_add_u64 v[126:127], v[24:25], 0, s[42:43]
	v_lshl_add_u64 v[138:139], v[2:3], 1, v[0:1]
	v_mov_b32_e32 v109, 0xf149f2ca
	s_mov_b32 s0, 35
	v_add_u32_e32 v161, v31, v32
	v_add_u32_e32 v162, v33, v12
	v_add_u32_e32 v163, v34, v22
	v_add_u32_e32 v164, v30, v13
	v_add_u32_e32 v165, v30, v35
	v_add_u32_e32 v116, v116, v23
	v_mov_b32_e32 v0, 0
	v_mov_b32_e32 v1, v108
	v_mov_b32_e32 v2, v108
	v_mov_b32_e32 v3, v108
	v_mov_b32_e32 v4, v108
	v_mov_b32_e32 v5, v108
	v_mov_b32_e32 v6, v108
	v_mov_b32_e32 v7, v108
	v_mov_b32_e32 v8, v108
	v_mov_b32_e32 v9, v108
	v_mov_b32_e32 v10, v108
	v_mov_b32_e32 v11, v108
	v_mov_b32_e32 v12, v108
	v_mov_b32_e32 v13, v108
	v_mov_b32_e32 v14, v108
	v_mov_b32_e32 v15, v108
	v_mov_b32_e32 v16, 0
	v_mov_b32_e32 v17, v108
	v_mov_b32_e32 v18, v108
	v_mov_b32_e32 v19, v108
	v_mov_b32_e32 v20, v108
	v_mov_b32_e32 v21, v108
	v_mov_b32_e32 v22, v108
	v_mov_b32_e32 v23, v108
	v_mov_b32_e32 v24, v108
	v_mov_b32_e32 v25, v108
	v_mov_b32_e32 v26, v108
	v_mov_b32_e32 v27, v108
	v_mov_b32_e32 v28, v108
	v_mov_b32_e32 v29, v108
	v_mov_b32_e32 v30, v108
	v_mov_b32_e32 v31, v108
	s_waitcnt lgkmcnt(0)
	s_barrier
	v_mov_b32_e32 v253, 0x6000
	v_mov_b32_e32 v252, 0
.LBB0_1684:
	s_waitcnt lgkmcnt(0)
	s_waitcnt vmcnt(0)
	ds_write_b128 v161, v[224:227]
	ds_write_b128 v162, v[228:231]
	ds_write_b128 v163, v[232:235]
	ds_write_b128 v164, v[236:239] offset:13312
	ds_write_b128 v165, v[240:243] offset:13312
	s_waitcnt lgkmcnt(0)
	s_barrier
	ds_read_b128 v[32:35], v116
	ds_read_b128 v[88:91], v116 offset:32
	v_lshl_add_u64 v[100:101], s[8:9], 0, v[138:139]
	v_lshl_add_u64 v[144:145], s[8:9], 0, v[136:137]
	v_lshl_add_u64 v[102:103], s[8:9], 0, v[134:135]
	v_lshl_add_u64 v[106:107], s[8:9], 0, v[132:133]
	v_lshl_add_u64 v[104:105], s[8:9], 0, v[130:131]
	v_lshl_add_u64 v[140:141], s[8:9], 0, v[128:129]
	v_lshl_add_u64 v[142:143], s[8:9], 0, v[126:127]
	v_lshl_add_u64 v[146:147], s[8:9], 0, v[124:125]
	v_cndmask_b32_e32 v97, v145, v101, vcc
	v_cndmask_b32_e32 v96, v144, v100, vcc
	v_cndmask_b32_e64 v99, v107, v103, s[4:5]
	v_cndmask_b32_e64 v98, v106, v102, s[4:5]
	v_cndmask_b32_e64 v145, v141, v105, s[6:7]
	v_cndmask_b32_e64 v144, v140, v104, s[6:7]
	global_load_dwordx4 v[236:239], v[142:143], off
	global_load_dwordx4 v[240:243], v[146:147], off
	global_load_dwordx4 v[224:227], v[96:97], off
	global_load_dwordx4 v[228:231], v[98:99], off
	global_load_dwordx4 v[232:235], v[144:145], off
	s_waitcnt lgkmcnt(1)
	v_mfma_f32_32x32x16_bf16 v[32:47], v[32:35], v[84:87], 0
	ds_read_b128 v[48:51], v116 offset:6656
	ds_read_b128 v[92:95], v116 offset:6688
	v_mov_b32_e32 v167, v109
	v_mov_b32_e32 v166, v108
	s_waitcnt lgkmcnt(1)
	v_mfma_f32_32x32x16_bf16 v[48:63], v[48:51], v[84:87], 0
	v_add_u32_e32 v172, v122, v159
	v_add_u32_e32 v173, v122, v160
	s_add_i32 s0, s0, -1
	v_mfma_f32_32x32x16_bf16 v[32:47], v[88:91], v[80:83], v[32:47]
	ds_read_b128 v[88:91], v116 offset:64
	v_lshl_add_u64 v[124:125], v[124:125], 0, s[44:45]
	v_lshl_add_u64 v[126:127], v[126:127], 0, s[44:45]
	v_lshl_add_u64 v[128:129], v[128:129], 0, s[46:47]
	v_lshl_add_u64 v[130:131], v[130:131], 0, s[48:49]
	v_lshl_add_u64 v[132:133], v[132:133], 0, s[46:47]
	v_lshl_add_u64 v[134:135], v[134:135], 0, s[48:49]
	s_waitcnt lgkmcnt(1)
	v_mfma_f32_32x32x16_bf16 v[48:63], v[92:95], v[80:83], v[48:63]
	ds_read_b128 v[168:171], v116 offset:96
	ds_read_b128 v[92:95], v116 offset:6720
	ds_read_b128 v[96:99], v116 offset:6752
	v_lshl_add_u64 v[136:137], v[136:137], 0, s[46:47]
	v_lshl_add_u64 v[138:139], v[138:139], 0, s[48:49]
	s_cmp_lg_u32 s0, 0
	s_waitcnt lgkmcnt(3)
	v_mfma_f32_32x32x16_bf16 v[32:47], v[88:91], v[76:79], v[32:47]
	s_waitcnt lgkmcnt(1)
	v_mfma_f32_32x32x16_bf16 v[48:63], v[92:95], v[76:79], v[48:63]
	ds_read_b128 v[92:95], v116 offset:128
	ds_read_b128 v[112:115], v116 offset:160
	ds_read_b128 v[88:91], v116 offset:6784
	ds_read_b128 v[108:111], v116 offset:6816
	v_mfma_f32_32x32x16_bf16 v[32:47], v[168:171], v[72:75], v[32:47]
	v_add_u32_e32 v168, v158, v159
	v_add_u32_e32 v169, v158, v160
	s_waitcnt lgkmcnt(4)
	v_mfma_f32_32x32x16_bf16 v[48:63], v[96:99], v[72:75], v[48:63]
	s_waitcnt lgkmcnt(0)
	v_mfma_f32_32x32x16_bf16 v[32:47], v[92:95], v[68:71], v[32:47]
	v_add_u32_e32 v143, 0x3000, v172
	v_add_u32_e32 v143, v252, v143
	v_add_u32_e32 v142, 0x3000, v173
	v_add_u32_e32 v142, v252, v142
	v_add_u32_e32 v141, 0x3000, v168
	v_add_u32_e32 v141, v252, v141
	v_add_u32_e32 v140, 0x3000, v169
	v_add_u32_e32 v140, v252, v140
	v_mfma_f32_32x32x16_bf16 v[48:63], v[88:91], v[68:71], v[48:63]
	s_nop 0
	ds_read2_b64 v[144:147], v143 offset0:128 offset1:130
	v_mfma_f32_32x32x16_bf16 v[32:47], v[112:115], v[64:67], v[32:47]
	ds_read2_b64 v[112:115], v143 offset0:132 offset1:134
	ds_read2_b64 v[168:171], v142 offset0:128 offset1:130
	ds_read2_b64 v[172:175], v142 offset0:132 offset1:134
	ds_read2_b64 v[176:179], v143 offset0:136 offset1:138
	ds_read2_b64 v[180:183], v142 offset0:136 offset1:138
	ds_read2_b64 v[184:187], v141 offset0:140 offset1:142
	ds_read2_b64 v[188:191], v140 offset0:140 offset1:142
	v_mfma_f32_32x32x16_bf16 v[48:63], v[108:111], v[64:67], v[48:63]
	s_nop 3
	v_max_f32_e32 v108, v33, v33
	v_max_f32_e32 v109, v32, v32
	v_max_f32_e32 v108, v109, v108
	v_max3_f32 v108, v108, v34, v35
	v_max3_f32 v108, v108, v36, v37
	v_max3_f32 v108, v108, v38, v39
	v_max3_f32 v108, v108, v40, v41
	v_max3_f32 v108, v108, v42, v43
	v_max3_f32 v108, v108, v44, v45
	v_max3_f32 v108, v108, v46, v47
	v_max3_f32 v108, v108, v48, v49
	v_max3_f32 v108, v108, v50, v51
	v_max3_f32 v108, v108, v52, v53
	v_max3_f32 v108, v108, v54, v55
	v_max3_f32 v108, v108, v56, v57
	v_max3_f32 v108, v108, v58, v59
	v_max3_f32 v108, v108, v60, v61
	v_max3_f32 v108, v108, v62, v63
	ds_bpermute_b32 v109, v123, v108
	s_waitcnt lgkmcnt(0)
	v_max3_f32 v109, v167, v108, v109
	v_sub_f32_e32 v108, v167, v109
	v_sub_f32_e32 v32, v32, v109
	v_sub_f32_e32 v33, v33, v109
	v_sub_f32_e32 v34, v34, v109
	v_sub_f32_e32 v35, v35, v109
	v_sub_f32_e32 v36, v36, v109
	v_sub_f32_e32 v37, v37, v109
	v_sub_f32_e32 v38, v38, v109
	v_sub_f32_e32 v39, v39, v109
	v_sub_f32_e32 v110, v42, v109
	v_exp_f32_e32 v42, v108
	v_exp_f32_e32 v32, v32
	v_exp_f32_e32 v33, v33
	s_nop 0
	v_cvt_pk_bf16_f32 v244, v32, v33
	v_exp_f32_e32 v108, v34
	v_exp_f32_e32 v111, v35
	v_exp_f32_e32 v167, v36
	v_exp_f32_e32 v192, v37
	v_exp_f32_e32 v193, v38
	v_exp_f32_e32 v194, v39
	v_sub_f32_e32 v43, v43, v109
	v_sub_f32_e32 v40, v40, v109
	v_sub_f32_e32 v41, v41, v109
	v_exp_f32_e32 v43, v43
	v_exp_f32_e32 v195, v40
	v_exp_f32_e32 v196, v41
	v_add_f32_e32 v34, 0, v32
	v_bfe_u32 v39, v32, 16, 1
	v_add_f32_e32 v222, v33, v34
	v_add3_u32 v32, v32, v39, s61
	v_lshrrev_b32_e32 v32, 16, v32
	v_sub_f32_e32 v44, v44, v109
	v_sub_f32_e32 v45, v45, v109
	v_sub_f32_e32 v46, v46, v109
	v_pk_mul_f32 v[30:31], v[30:31], v[42:43] op_sel_hi:[1,0]
	v_pk_mul_f32 v[28:29], v[28:29], v[42:43] op_sel_hi:[1,0]
	v_pk_mul_f32 v[26:27], v[26:27], v[42:43] op_sel_hi:[1,0]
	v_pk_mul_f32 v[24:25], v[24:25], v[42:43] op_sel_hi:[1,0]
	v_pk_mul_f32 v[22:23], v[22:23], v[42:43] op_sel_hi:[1,0]
	v_pk_mul_f32 v[20:21], v[20:21], v[42:43] op_sel_hi:[1,0]
	v_pk_mul_f32 v[18:19], v[18:19], v[42:43] op_sel_hi:[1,0]
	v_pk_mul_f32 v[16:17], v[16:17], v[42:43] op_sel_hi:[1,0]
	v_pk_mul_f32 v[14:15], v[14:15], v[42:43] op_sel_hi:[1,0]
	v_pk_mul_f32 v[12:13], v[12:13], v[42:43] op_sel_hi:[1,0]
	v_pk_mul_f32 v[10:11], v[10:11], v[42:43] op_sel_hi:[1,0]
	v_pk_mul_f32 v[8:9], v[8:9], v[42:43] op_sel_hi:[1,0]
	v_pk_mul_f32 v[6:7], v[6:7], v[42:43] op_sel_hi:[1,0]
	v_pk_mul_f32 v[4:5], v[4:5], v[42:43] op_sel_hi:[1,0]
	v_pk_mul_f32 v[2:3], v[2:3], v[42:43] op_sel_hi:[1,0]
	v_pk_mul_f32 v[0:1], v[0:1], v[42:43] op_sel_hi:[1,0]
	v_cvt_pk_bf16_f32 v35, v193, v194
	v_cvt_pk_bf16_f32 v34, v167, v192
	v_cvt_pk_bf16_f32 v33, v108, v111
	v_mov_b32_e32 v32, v244
	v_sub_f32_e32 v47, v47, v109
	v_exp_f32_e32 v110, v110
	v_exp_f32_e32 v44, v44
	v_exp_f32_e32 v45, v45
	v_exp_f32_e32 v46, v46
	v_mfma_f32_32x32x16_bf16 v[16:31], v[144:147], v[32:35], v[16:31]
	v_exp_f32_e32 v47, v47
	v_bfe_u32 v199, v45, 16, 1
	v_bfe_u32 v202, v195, 16, 1
	v_bfe_u32 v203, v110, 16, 1
	v_bfe_u32 v204, v44, 16, 1
	v_mfma_f32_32x32x16_bf16 v[0:15], v[168:171], v[32:35], v[0:15]
	v_bfe_u32 v205, v46, 16, 1
	v_bfe_u32 v198, v47, 16, 1
	v_add3_u32 v197, v45, v199, s61
	v_add3_u32 v199, v46, v205, s61
	v_add3_u32 v200, v44, v204, s61
	v_add3_u32 v201, v110, v203, s61
	v_add3_u32 v202, v195, v202, s61
	v_add3_u32 v198, v47, v198, s61
	v_add_f32_e32 v37, v108, v222
	v_lshrrev_b32_e32 v144, 16, v199
	v_cvt_pk_bf16_f32 v35, v46, v47
	v_cvt_pk_bf16_f32 v34, v44, v45
	v_cvt_pk_bf16_f32 v33, v110, v43
	v_cvt_pk_bf16_f32 v32, v195, v196
	v_add_f32_e32 v108, v111, v37
	v_sub_f32_e32 v48, v48, v109
	v_mfma_f32_32x32x16_bf16 v[16:31], v[112:115], v[32:35], v[16:31]
	v_sub_f32_e32 v49, v49, v109
	v_sub_f32_e32 v50, v50, v109
	v_sub_f32_e32 v51, v51, v109
	v_sub_f32_e32 v52, v52, v109
	v_sub_f32_e32 v53, v53, v109
	v_sub_f32_e32 v54, v54, v109
	v_sub_f32_e32 v55, v55, v109
	v_mfma_f32_32x32x16_bf16 v[0:15], v[172:175], v[32:35], v[0:15]
	v_add_f32_e32 v32, v167, v108
	v_add_f32_e32 v32, v192, v32
	v_add_f32_e32 v32, v193, v32
	v_add_f32_e32 v32, v194, v32
	v_add_f32_e32 v32, v195, v32
	v_sub_f32_e32 v56, v56, v109
	v_exp_f32_e32 v48, v48
	v_exp_f32_e32 v49, v49
	v_exp_f32_e32 v50, v50
	v_exp_f32_e32 v51, v51
	v_exp_f32_e32 v52, v52
	v_exp_f32_e32 v53, v53
	v_exp_f32_e32 v54, v54
	v_add_f32_e32 v32, v196, v32
	v_exp_f32_e32 v55, v55
	v_exp_f32_e32 v56, v56
	v_add_f32_e32 v32, v110, v32
	v_add_f32_e32 v32, v43, v32
	v_add_f32_e32 v32, v44, v32
	v_bfe_u32 v207, v53, 16, 1
	v_bfe_u32 v208, v51, 16, 1
	v_bfe_u32 v209, v49, 16, 1
	v_bfe_u32 v210, v48, 16, 1
	v_bfe_u32 v211, v50, 16, 1
	v_bfe_u32 v212, v52, 16, 1
	v_bfe_u32 v213, v54, 16, 1
	v_add_f32_e32 v32, v45, v32
	v_bfe_u32 v206, v55, 16, 1
	v_bfe_u32 v218, v56, 16, 1
	v_add3_u32 v203, v49, v209, s61
	v_add3_u32 v204, v51, v208, s61
	v_add3_u32 v205, v53, v207, s61
	v_add3_u32 v207, v54, v213, s61
	v_add3_u32 v208, v52, v212, s61
	v_add3_u32 v209, v50, v211, s61
	v_add3_u32 v210, v48, v210, s61
	v_add_f32_e32 v32, v46, v32
	v_add3_u32 v206, v55, v206, s61
	v_lshrrev_b32_e32 v145, 16, v210
	v_lshrrev_b32_e32 v146, 16, v209
	v_lshrrev_b32_e32 v147, 16, v208
	v_lshrrev_b32_e32 v168, 16, v207
	v_add_f32_e32 v32, v47, v32
	v_sub_f32_e32 v57, v57, v109
	v_sub_f32_e32 v58, v58, v109
	v_sub_f32_e32 v59, v59, v109
	v_sub_f32_e32 v60, v60, v109
	v_sub_f32_e32 v61, v61, v109
	v_sub_f32_e32 v62, v62, v109
	v_cvt_pk_bf16_f32 v37, v54, v55
	v_cvt_pk_bf16_f32 v36, v52, v53
	v_cvt_pk_bf16_f32 v35, v50, v51
	v_cvt_pk_bf16_f32 v34, v48, v49
	v_add_f32_e32 v32, v48, v32
	v_sub_f32_e32 v63, v63, v109
	v_exp_f32_e32 v57, v57
	v_exp_f32_e32 v58, v58
	v_exp_f32_e32 v59, v59
	v_exp_f32_e32 v60, v60
	v_exp_f32_e32 v61, v61
	v_exp_f32_e32 v62, v62
	v_mfma_f32_32x32x16_bf16 v[16:31], v[176:179], v[34:37], v[16:31]
	v_add_f32_e32 v32, v49, v32
	v_exp_f32_e32 v63, v63
	v_add_f32_e32 v32, v50, v32
	v_add_f32_e32 v32, v51, v32
	v_add_f32_e32 v32, v52, v32
	v_bfe_u32 v215, v61, 16, 1
	v_bfe_u32 v216, v59, 16, 1
	v_mfma_f32_32x32x16_bf16 v[0:15], v[180:183], v[34:37], v[0:15]
	v_bfe_u32 v217, v57, 16, 1
	v_bfe_u32 v219, v58, 16, 1
	v_bfe_u32 v220, v60, 16, 1
	v_bfe_u32 v221, v62, 16, 1
	v_add_f32_e32 v32, v53, v32
	v_bfe_u32 v214, v63, 16, 1
	v_add3_u32 v211, v57, v217, s61
	v_add3_u32 v212, v59, v216, s61
	v_add3_u32 v213, v61, v215, s61
	v_add3_u32 v215, v62, v221, s61
	v_add3_u32 v216, v60, v220, s61
	v_add3_u32 v217, v58, v219, s61
	v_add_f32_e32 v32, v54, v32
	v_add3_u32 v214, v63, v214, s61
	v_add_f32_e32 v32, v55, v32
	v_cvt_pk_bf16_f32 v41, v62, v63
	v_cvt_pk_bf16_f32 v40, v60, v61
	v_cvt_pk_bf16_f32 v39, v58, v59
	v_cvt_pk_bf16_f32 v38, v56, v57
	v_add_f32_e32 v32, v56, v32
	v_add_f32_e32 v32, v57, v32
	v_mfma_f32_32x32x16_bf16 v[16:31], v[184:187], v[38:41], v[16:31]
	v_add_f32_e32 v32, v58, v32
	v_add_f32_e32 v32, v59, v32
	v_add_f32_e32 v32, v60, v32
	v_add_f32_e32 v32, v61, v32
	v_add_f32_e32 v32, v62, v32
	v_add_f32_e32 v108, v63, v32
	v_fmac_f32_e32 v108, v166, v42
	v_mfma_f32_32x32x16_bf16 v[0:15], v[188:191], v[38:41], v[0:15]
	v_add_u32_e32 v116, v253, v116
	v_add_u32_e32 v161, v253, v161
	v_add_u32_e32 v162, v253, v162
	v_add_u32_e32 v163, v253, v163
	v_add_u32_e32 v164, v253, v164
	v_add_u32_e32 v165, v253, v165
	v_add_u32_e32 v140, v253, v140
	v_add_u32_e32 v141, v253, v141
	v_add_u32_e32 v142, v253, v142
	v_add_u32_e32 v143, v253, v143
	v_add_u32_e32 v252, v253, v252
	v_sub_u32_e32 v253, 0, v253
	s_cbranch_scc1 .LBB0_1684
	s_waitcnt vmcnt(0)
	ds_write_b128 v161, v[224:227]
	ds_write_b128 v162, v[228:231]
	ds_write_b128 v163, v[232:235]
	ds_write_b128 v164, v[236:239] offset:13312
	ds_write_b128 v165, v[240:243] offset:13312
	s_waitcnt lgkmcnt(0)
	s_barrier
	ds_read_b128 v[32:35], v116
	ds_read_b128 v[36:39], v116 offset:32
	s_waitcnt lgkmcnt(1)
	v_mfma_f32_32x32x16_bf16 v[48:63], v[32:35], v[84:87], 0
	s_waitcnt lgkmcnt(0)
	v_mfma_f32_32x32x16_bf16 v[48:63], v[36:39], v[80:83], v[48:63]
	ds_read_b128 v[32:35], v116 offset:64
	ds_read_b128 v[36:39], v116 offset:96
	s_waitcnt lgkmcnt(1)
	v_mfma_f32_32x32x16_bf16 v[48:63], v[32:35], v[76:79], v[48:63]
	s_waitcnt lgkmcnt(0)
	v_mfma_f32_32x32x16_bf16 v[48:63], v[36:39], v[72:75], v[48:63]
	ds_read_b128 v[32:35], v116 offset:128
	ds_read_b128 v[36:39], v116 offset:160
	s_waitcnt lgkmcnt(1)
	v_mfma_f32_32x32x16_bf16 v[48:63], v[32:35], v[68:71], v[48:63]
	ds_read_b128 v[32:35], v116 offset:6656
	ds_read_b128 v[88:91], v116 offset:6688
	s_waitcnt lgkmcnt(2)
	v_mfma_f32_32x32x16_bf16 v[48:63], v[36:39], v[64:67], v[48:63]
	s_waitcnt lgkmcnt(1)
	v_mfma_f32_32x32x16_bf16 v[32:47], v[32:35], v[84:87], 0
	s_waitcnt lgkmcnt(0)
	v_mfma_f32_32x32x16_bf16 v[32:47], v[88:91], v[80:83], v[32:47]
	ds_read_b128 v[80:83], v116 offset:6720
	ds_read_b128 v[84:87], v116 offset:6752
	s_waitcnt lgkmcnt(1)
	v_mfma_f32_32x32x16_bf16 v[32:47], v[80:83], v[76:79], v[32:47]
	s_nop 3
	v_max_f32_e32 v80, v49, v49
	v_max_f32_e32 v81, v48, v48
	v_max_f32_e32 v80, v81, v80
	s_waitcnt lgkmcnt(0)
	v_mfma_f32_32x32x16_bf16 v[32:47], v[84:87], v[72:75], v[32:47]
	ds_read_b128 v[72:75], v116 offset:6784
	ds_read_b128 v[76:79], v116 offset:6816
	s_waitcnt lgkmcnt(1)
	v_mfma_f32_32x32x16_bf16 v[32:47], v[72:75], v[68:71], v[32:47]
	v_max3_f32 v68, v80, v50, v51
	v_max3_f32 v68, v68, v52, v53
	v_max3_f32 v68, v68, v54, v55
	v_max3_f32 v68, v68, v56, v57
	v_max3_f32 v68, v68, v58, v59
	v_max3_f32 v68, v68, v60, v61
	v_max3_f32 v68, v68, v62, v63
	s_waitcnt lgkmcnt(0)
	v_mfma_f32_32x32x16_bf16 v[32:47], v[76:79], v[64:67], v[32:47]
	s_nop 11
	v_max3_f32 v64, v68, v32, v33
	v_max3_f32 v64, v64, v34, v35
	v_max3_f32 v64, v64, v36, v37
	v_max3_f32 v64, v64, v38, v39
	v_max3_f32 v64, v64, v40, v41
	v_max3_f32 v64, v64, v42, v43
	v_max3_f32 v64, v64, v44, v45
	v_max3_f32 v64, v64, v46, v47
	ds_bpermute_b32 v65, v123, v64
	s_waitcnt lgkmcnt(0)
	v_max3_f32 v65, v109, v64, v65
	v_sub_f32_e32 v32, v32, v65
	v_exp_f32_e32 v66, v32
	v_sub_f32_e32 v32, v33, v65
	v_exp_f32_e32 v67, v32
	v_sub_f32_e32 v32, v34, v65
	v_exp_f32_e32 v68, v32
	v_sub_f32_e32 v32, v35, v65
	v_exp_f32_e32 v69, v32
	v_sub_f32_e32 v32, v36, v65
	v_exp_f32_e32 v70, v32
	v_sub_f32_e32 v32, v37, v65
	v_exp_f32_e32 v71, v32
	v_sub_f32_e32 v32, v38, v65
	v_exp_f32_e32 v72, v32
	v_sub_f32_e32 v32, v39, v65
	v_exp_f32_e32 v73, v32
	v_sub_f32_e32 v32, v40, v65
	v_exp_f32_e32 v74, v32
	v_sub_f32_e32 v32, v41, v65
	v_exp_f32_e32 v75, v32
	v_sub_f32_e32 v32, v42, v65
	v_sub_f32_e32 v48, v48, v65
	v_exp_f32_e32 v76, v32
	v_sub_f32_e32 v32, v43, v65
	v_exp_f32_e32 v48, v48
	v_sub_f32_e32 v49, v49, v65
	v_exp_f32_e32 v77, v32
	v_sub_f32_e32 v32, v44, v65
	v_exp_f32_e32 v49, v49
	v_sub_f32_e32 v50, v50, v65
	v_sub_f32_e32 v55, v55, v65
	v_exp_f32_e32 v78, v32
	v_sub_f32_e32 v32, v45, v65
	v_exp_f32_e32 v50, v50
	v_sub_f32_e32 v51, v51, v65
	v_sub_f32_e32 v53, v53, v65
	v_exp_f32_e32 v55, v55
	v_exp_f32_e32 v79, v32
	v_sub_f32_e32 v32, v46, v65
	v_exp_f32_e32 v51, v51
	v_sub_f32_e32 v52, v52, v65
	v_exp_f32_e32 v53, v53
	v_sub_f32_e32 v54, v54, v65
	v_exp_f32_e32 v80, v32
	v_sub_f32_e32 v32, v47, v65
	v_sub_f32_e32 v64, v109, v65
	v_exp_f32_e32 v52, v52
	v_exp_f32_e32 v54, v54
	v_sub_f32_e32 v56, v56, v65
	v_sub_f32_e32 v57, v57, v65
	v_sub_f32_e32 v58, v58, v65
	v_sub_f32_e32 v59, v59, v65
	v_sub_f32_e32 v60, v60, v65
	v_sub_f32_e32 v61, v61, v65
	v_sub_f32_e32 v62, v62, v65
	v_sub_f32_e32 v63, v63, v65
	v_exp_f32_e32 v65, v32
	v_add_f32_e32 v32, 0, v48
	v_add_f32_e32 v32, v49, v32
	v_add_f32_e32 v44, v50, v32
	ds_read2_b64 v[32:35], v143 offset0:128 offset1:130
	v_exp_f32_e32 v64, v64
	v_cvt_pk_bf16_f32 v39, v54, v55
	v_cvt_pk_bf16_f32 v38, v52, v53
	v_cvt_pk_bf16_f32 v37, v50, v51
	v_cvt_pk_bf16_f32 v36, v48, v49
	ds_read2_b64 v[40:43], v142 offset0:128 offset1:130
	v_pk_mul_f32 v[30:31], v[30:31], v[64:65] op_sel_hi:[1,0]
	v_pk_mul_f32 v[28:29], v[28:29], v[64:65] op_sel_hi:[1,0]
	v_pk_mul_f32 v[26:27], v[26:27], v[64:65] op_sel_hi:[1,0]
	v_pk_mul_f32 v[24:25], v[24:25], v[64:65] op_sel_hi:[1,0]
	v_pk_mul_f32 v[22:23], v[22:23], v[64:65] op_sel_hi:[1,0]
	v_pk_mul_f32 v[20:21], v[20:21], v[64:65] op_sel_hi:[1,0]
	v_pk_mul_f32 v[18:19], v[18:19], v[64:65] op_sel_hi:[1,0]
	v_pk_mul_f32 v[16:17], v[16:17], v[64:65] op_sel_hi:[1,0]
	v_exp_f32_e32 v57, v57
	v_exp_f32_e32 v59, v59
	s_waitcnt lgkmcnt(1)
	v_mfma_f32_32x32x16_bf16 v[16:31], v[32:35], v[36:39], v[16:31]
	v_add_f32_e32 v32, v51, v44
	v_exp_f32_e32 v56, v56
	v_exp_f32_e32 v58, v58
	v_exp_f32_e32 v60, v60
	v_exp_f32_e32 v62, v62
	v_add_f32_e32 v32, v52, v32
	v_exp_f32_e32 v61, v61
	v_exp_f32_e32 v63, v63
	v_add_f32_e32 v32, v53, v32
	v_pk_mul_f32 v[14:15], v[14:15], v[64:65] op_sel_hi:[1,0]
	v_pk_mul_f32 v[12:13], v[12:13], v[64:65] op_sel_hi:[1,0]
	v_pk_mul_f32 v[10:11], v[10:11], v[64:65] op_sel_hi:[1,0]
	v_pk_mul_f32 v[8:9], v[8:9], v[64:65] op_sel_hi:[1,0]
	v_pk_mul_f32 v[6:7], v[6:7], v[64:65] op_sel_hi:[1,0]
	v_pk_mul_f32 v[4:5], v[4:5], v[64:65] op_sel_hi:[1,0]
	v_pk_mul_f32 v[2:3], v[2:3], v[64:65] op_sel_hi:[1,0]
	v_pk_mul_f32 v[0:1], v[0:1], v[64:65] op_sel_hi:[1,0]
	v_add_f32_e32 v32, v54, v32
	v_add_f32_e32 v48, v55, v32
	s_waitcnt lgkmcnt(0)
	v_mfma_f32_32x32x16_bf16 v[0:15], v[40:43], v[36:39], v[0:15]
	ds_read2_b64 v[32:35], v143 offset0:132 offset1:134
	ds_read2_b64 v[44:47], v142 offset0:132 offset1:134
	v_add_f32_e32 v40, v56, v48
	v_bfe_u32 v38, v56, 16, 1
	v_bfe_u32 v39, v58, 16, 1
	v_bfe_u32 v48, v62, 16, 1
	v_add3_u32 v48, v62, v48, s61
	v_add3_u32 v39, v58, v39, s61
	v_add3_u32 v38, v56, v38, s61
	v_lshrrev_b32_e32 v49, 16, v38
	v_lshrrev_b32_e32 v50, 16, v39
	v_cvt_pk_bf16_f32 v39, v62, v63
	v_cvt_pk_bf16_f32 v38, v60, v61
	v_cvt_pk_bf16_f32 v37, v58, v59
	v_cvt_pk_bf16_f32 v36, v56, v57
	s_waitcnt lgkmcnt(1)
	s_nop 0
	v_mfma_f32_32x32x16_bf16 v[16:31], v[32:35], v[36:39], v[16:31]
	v_add_f32_e32 v32, v57, v40
	v_add_f32_e32 v32, v58, v32
	v_add_f32_e32 v32, v59, v32
	v_add_f32_e32 v32, v60, v32
	v_add_f32_e32 v32, v61, v32
	v_add_f32_e32 v32, v62, v32
	v_add_f32_e32 v32, v63, v32
	s_waitcnt lgkmcnt(0)
	v_mfma_f32_32x32x16_bf16 v[0:15], v[44:47], v[36:39], v[0:15]
	v_add_f32_e32 v44, v66, v32
	ds_read2_b64 v[32:35], v143 offset0:136 offset1:138
	v_cvt_pk_bf16_f32 v39, v72, v73
	v_cvt_pk_bf16_f32 v38, v70, v71
	v_cvt_pk_bf16_f32 v37, v68, v69
	v_cvt_pk_bf16_f32 v36, v66, v67
	ds_read2_b64 v[40:43], v142 offset0:136 offset1:138
	s_waitcnt lgkmcnt(1)
	v_mfma_f32_32x32x16_bf16 v[16:31], v[32:35], v[36:39], v[16:31]
	v_add_f32_e32 v32, v67, v44
	v_add_f32_e32 v32, v68, v32
	v_add_f32_e32 v32, v69, v32
	v_add_f32_e32 v32, v70, v32
	v_add_f32_e32 v32, v71, v32
	v_add_f32_e32 v32, v72, v32
	v_add_f32_e32 v32, v73, v32
	v_add_f32_e32 v32, v74, v32
	v_add_f32_e32 v32, v75, v32
	v_add_f32_e32 v32, v76, v32
	v_add_f32_e32 v32, v77, v32
	v_add_f32_e32 v32, v78, v32
	v_add_f32_e32 v32, v79, v32
	v_add_f32_e32 v32, v80, v32
	s_waitcnt lgkmcnt(0)
	v_mfma_f32_32x32x16_bf16 v[0:15], v[40:43], v[36:39], v[0:15]
	v_add_f32_e32 v40, v65, v32
	v_bfe_u32 v32, v74, 16, 1
	v_bfe_u32 v33, v76, 16, 1
	v_add3_u32 v33, v76, v33, s61
	v_add3_u32 v32, v74, v32, s61
	v_lshrrev_b32_e32 v43, 16, v32
	v_lshrrev_b32_e32 v44, 16, v33
	ds_read2_b64 v[32:35], v141 offset0:140 offset1:142
	v_fmac_f32_e32 v40, v108, v64
	v_cvt_pk_bf16_f32 v39, v80, v65
	ds_bpermute_b32 v41, v123, v40
	v_cvt_pk_bf16_f32 v38, v78, v79
	v_cvt_pk_bf16_f32 v37, v76, v77
	v_cvt_pk_bf16_f32 v36, v74, v75
	v_mov_b32_e32 v123, v117
	s_waitcnt lgkmcnt(0)
	v_add_f32_e32 v40, v40, v41
	v_mfma_f32_32x32x16_bf16 v[16:31], v[32:35], v[36:39], v[16:31]
	ds_read2_b64 v[32:35], v140 offset0:140 offset1:142
	v_div_scale_f32 v41, s[0:1], v40, v40, 1.0
	v_rcp_f32_e32 v42, v41
	s_waitcnt lgkmcnt(0)
	v_mfma_f32_32x32x16_bf16 v[0:15], v[32:35], v[36:39], v[0:15]
	v_fma_f32 v32, -v41, v42, 1.0
	v_fmac_f32_e32 v42, v32, v42
	v_div_scale_f32 v32, vcc, 1.0, v40, 1.0
	v_mul_f32_e32 v33, v32, v42
	v_fma_f32 v34, -v41, v33, v32
	v_fmac_f32_e32 v33, v34, v42
	v_fma_f32 v32, -v41, v33, v32
	v_div_fmas_f32 v32, v32, v42, v33
	v_div_fixup_f32 v32, v32, v40, 1.0
	v_mov_b32_e32 v38, v16
	v_mov_b32_e32 v39, v18
	v_mov_b32_e32 v18, v17
	v_lshlrev_b64 v[34:35], 11, v[118:119]
	v_pk_mul_f32 v[38:39], v[38:39], v[32:33] op_sel_hi:[1,0]
	v_pk_mul_f32 v[16:17], v[18:19], v[32:33] op_sel_hi:[1,0]
	v_lshl_add_u64 v[34:35], s[8:9], 0, v[34:35]
	v_and_b32_sdwa v19, v38, v155 dst_sel:DWORD dst_unused:UNUSED_PAD src0_sel:WORD_1 src1_sel:DWORD
	v_and_b32_sdwa v33, v17, v155 dst_sel:DWORD dst_unused:UNUSED_PAD src0_sel:WORD_1 src1_sel:DWORD
	v_lshl_add_u64 v[34:35], v[120:121], 1, v[34:35]
	v_and_b32_sdwa v18, v39, v155 dst_sel:DWORD dst_unused:UNUSED_PAD src0_sel:WORD_1 src1_sel:DWORD
	v_add3_u32 v19, v38, v19, s61
	v_and_b32_sdwa v38, v16, v155 dst_sel:DWORD dst_unused:UNUSED_PAD src0_sel:WORD_1 src1_sel:DWORD
	v_add3_u32 v17, v17, v33, s61
	v_lshl_add_u64 v[34:35], v[34:35], 0, v[122:123]
	v_add3_u32 v18, v39, v18, s61
	v_add3_u32 v16, v16, v38, s61
	v_and_b32_e32 v17, 0xffff0000, v17
	v_and_b32_e32 v16, 0xffff0000, v16
	v_or_b32_sdwa v17, v17, v18 dst_sel:DWORD dst_unused:UNUSED_PAD src0_sel:DWORD src1_sel:WORD_1
	v_add_co_u32_e32 v18, vcc, s63, v34
	v_or_b32_sdwa v16, v16, v19 dst_sel:DWORD dst_unused:UNUSED_PAD src0_sel:DWORD src1_sel:WORD_1
	s_nop 0
	v_addc_co_u32_e32 v19, vcc, 0, v35, vcc
	global_store_dwordx2 v[18:19], v[16:17], off offset:3840
	v_mov_b32_e32 v16, v20
	v_mov_b32_e32 v17, v22
	v_pk_mul_f32 v[16:17], v[16:17], v[32:33] op_sel_hi:[1,0]
	v_mov_b32_e32 v22, v21
	v_pk_mul_f32 v[18:19], v[22:23], v[32:33] op_sel_hi:[1,0]
	v_and_b32_sdwa v20, v17, v155 dst_sel:DWORD dst_unused:UNUSED_PAD src0_sel:WORD_1 src1_sel:DWORD
	v_and_b32_sdwa v21, v16, v155 dst_sel:DWORD dst_unused:UNUSED_PAD src0_sel:WORD_1 src1_sel:DWORD
	v_add3_u32 v16, v16, v21, s61
	v_add3_u32 v17, v17, v20, s61
	v_and_b32_sdwa v20, v19, v155 dst_sel:DWORD dst_unused:UNUSED_PAD src0_sel:WORD_1 src1_sel:DWORD
	v_and_b32_sdwa v21, v18, v155 dst_sel:DWORD dst_unused:UNUSED_PAD src0_sel:WORD_1 src1_sel:DWORD
	v_add3_u32 v19, v19, v20, s61
	v_add3_u32 v18, v18, v21, s61
	v_and_b32_e32 v19, 0xffff0000, v19
	v_and_b32_e32 v18, 0xffff0000, v18
	v_lshl_add_u64 v[36:37], v[34:35], 0, s[50:51]
	v_or_b32_sdwa v17, v19, v17 dst_sel:DWORD dst_unused:UNUSED_PAD src0_sel:DWORD src1_sel:WORD_1
	v_or_b32_sdwa v16, v18, v16 dst_sel:DWORD dst_unused:UNUSED_PAD src0_sel:DWORD src1_sel:WORD_1
	global_store_dwordx2 v[36:37], v[16:17], off offset:16
	v_mov_b32_e32 v16, v24
	v_mov_b32_e32 v17, v26
	v_pk_mul_f32 v[16:17], v[16:17], v[32:33] op_sel_hi:[1,0]
	v_mov_b32_e32 v26, v25
	v_pk_mul_f32 v[18:19], v[26:27], v[32:33] op_sel_hi:[1,0]
	v_and_b32_sdwa v20, v17, v155 dst_sel:DWORD dst_unused:UNUSED_PAD src0_sel:WORD_1 src1_sel:DWORD
	v_and_b32_sdwa v21, v16, v155 dst_sel:DWORD dst_unused:UNUSED_PAD src0_sel:WORD_1 src1_sel:DWORD
	v_add3_u32 v16, v16, v21, s61
	v_add3_u32 v17, v17, v20, s61
	v_and_b32_sdwa v20, v19, v155 dst_sel:DWORD dst_unused:UNUSED_PAD src0_sel:WORD_1 src1_sel:DWORD
	v_and_b32_sdwa v21, v18, v155 dst_sel:DWORD dst_unused:UNUSED_PAD src0_sel:WORD_1 src1_sel:DWORD
	v_add3_u32 v19, v19, v20, s61
	v_add3_u32 v18, v18, v21, s61
	v_and_b32_e32 v19, 0xffff0000, v19
	v_and_b32_e32 v18, 0xffff0000, v18
	v_or_b32_sdwa v17, v19, v17 dst_sel:DWORD dst_unused:UNUSED_PAD src0_sel:DWORD src1_sel:WORD_1
	v_or_b32_sdwa v16, v18, v16 dst_sel:DWORD dst_unused:UNUSED_PAD src0_sel:DWORD src1_sel:WORD_1
	global_store_dwordx2 v[36:37], v[16:17], off offset:32
	v_mov_b32_e32 v16, v28
	v_mov_b32_e32 v17, v30
	v_pk_mul_f32 v[16:17], v[16:17], v[32:33] op_sel_hi:[1,0]
	v_mov_b32_e32 v30, v29
	v_pk_mul_f32 v[18:19], v[30:31], v[32:33] op_sel_hi:[1,0]
	v_and_b32_sdwa v20, v17, v155 dst_sel:DWORD dst_unused:UNUSED_PAD src0_sel:WORD_1 src1_sel:DWORD
	v_and_b32_sdwa v21, v16, v155 dst_sel:DWORD dst_unused:UNUSED_PAD src0_sel:WORD_1 src1_sel:DWORD
	v_add3_u32 v16, v16, v21, s61
	v_add3_u32 v17, v17, v20, s61
	v_and_b32_sdwa v20, v19, v155 dst_sel:DWORD dst_unused:UNUSED_PAD src0_sel:WORD_1 src1_sel:DWORD
	v_and_b32_sdwa v21, v18, v155 dst_sel:DWORD dst_unused:UNUSED_PAD src0_sel:WORD_1 src1_sel:DWORD
	v_add3_u32 v19, v19, v20, s61
	v_add3_u32 v18, v18, v21, s61
	v_and_b32_e32 v19, 0xffff0000, v19
	v_and_b32_e32 v18, 0xffff0000, v18
	v_or_b32_sdwa v17, v19, v17 dst_sel:DWORD dst_unused:UNUSED_PAD src0_sel:DWORD src1_sel:WORD_1
	v_or_b32_sdwa v16, v18, v16 dst_sel:DWORD dst_unused:UNUSED_PAD src0_sel:DWORD src1_sel:WORD_1
	global_store_dwordx2 v[36:37], v[16:17], off offset:48
	v_mov_b32_e32 v16, v0
	v_mov_b32_e32 v17, v2
	v_pk_mul_f32 v[16:17], v[16:17], v[32:33] op_sel_hi:[1,0]
	v_mov_b32_e32 v2, v1
	v_pk_mul_f32 v[0:1], v[2:3], v[32:33] op_sel_hi:[1,0]
	v_and_b32_sdwa v2, v17, v155 dst_sel:DWORD dst_unused:UNUSED_PAD src0_sel:WORD_1 src1_sel:DWORD
	v_and_b32_sdwa v3, v16, v155 dst_sel:DWORD dst_unused:UNUSED_PAD src0_sel:WORD_1 src1_sel:DWORD
	v_add3_u32 v3, v16, v3, s61
	v_add3_u32 v2, v17, v2, s61
	v_and_b32_sdwa v16, v1, v155 dst_sel:DWORD dst_unused:UNUSED_PAD src0_sel:WORD_1 src1_sel:DWORD
	v_and_b32_sdwa v17, v0, v155 dst_sel:DWORD dst_unused:UNUSED_PAD src0_sel:WORD_1 src1_sel:DWORD
	v_add3_u32 v1, v1, v16, s61
	v_add3_u32 v0, v0, v17, s61
	v_and_b32_e32 v1, 0xffff0000, v1
	v_and_b32_e32 v0, 0xffff0000, v0
	v_or_b32_sdwa v1, v1, v2 dst_sel:DWORD dst_unused:UNUSED_PAD src0_sel:DWORD src1_sel:WORD_1
	v_or_b32_sdwa v0, v0, v3 dst_sel:DWORD dst_unused:UNUSED_PAD src0_sel:DWORD src1_sel:WORD_1
	global_store_dwordx2 v[36:37], v[0:1], off offset:64
	v_mov_b32_e32 v0, v4
	v_mov_b32_e32 v1, v6
	v_pk_mul_f32 v[0:1], v[0:1], v[32:33] op_sel_hi:[1,0]
	v_mov_b32_e32 v6, v5
	v_pk_mul_f32 v[2:3], v[6:7], v[32:33] op_sel_hi:[1,0]
	v_and_b32_sdwa v4, v1, v155 dst_sel:DWORD dst_unused:UNUSED_PAD src0_sel:WORD_1 src1_sel:DWORD
	v_and_b32_sdwa v5, v0, v155 dst_sel:DWORD dst_unused:UNUSED_PAD src0_sel:WORD_1 src1_sel:DWORD
	v_add3_u32 v0, v0, v5, s61
	v_add3_u32 v1, v1, v4, s61
	v_and_b32_sdwa v4, v3, v155 dst_sel:DWORD dst_unused:UNUSED_PAD src0_sel:WORD_1 src1_sel:DWORD
	v_and_b32_sdwa v5, v2, v155 dst_sel:DWORD dst_unused:UNUSED_PAD src0_sel:WORD_1 src1_sel:DWORD
	v_add3_u32 v3, v3, v4, s61
	v_add3_u32 v2, v2, v5, s61
	v_and_b32_e32 v3, 0xffff0000, v3
	v_and_b32_e32 v2, 0xffff0000, v2
	v_or_b32_sdwa v1, v3, v1 dst_sel:DWORD dst_unused:UNUSED_PAD src0_sel:DWORD src1_sel:WORD_1
	v_or_b32_sdwa v0, v2, v0 dst_sel:DWORD dst_unused:UNUSED_PAD src0_sel:DWORD src1_sel:WORD_1
	global_store_dwordx2 v[36:37], v[0:1], off offset:80
	v_mov_b32_e32 v0, v8
	v_mov_b32_e32 v1, v10
	v_pk_mul_f32 v[0:1], v[0:1], v[32:33] op_sel_hi:[1,0]
	v_mov_b32_e32 v10, v9
	v_pk_mul_f32 v[2:3], v[10:11], v[32:33] op_sel_hi:[1,0]
	v_and_b32_sdwa v4, v1, v155 dst_sel:DWORD dst_unused:UNUSED_PAD src0_sel:WORD_1 src1_sel:DWORD
	v_and_b32_sdwa v5, v0, v155 dst_sel:DWORD dst_unused:UNUSED_PAD src0_sel:WORD_1 src1_sel:DWORD
	v_add3_u32 v0, v0, v5, s61
	v_add3_u32 v1, v1, v4, s61
	v_and_b32_sdwa v4, v3, v155 dst_sel:DWORD dst_unused:UNUSED_PAD src0_sel:WORD_1 src1_sel:DWORD
	v_and_b32_sdwa v5, v2, v155 dst_sel:DWORD dst_unused:UNUSED_PAD src0_sel:WORD_1 src1_sel:DWORD
	v_add3_u32 v3, v3, v4, s61
	v_add3_u32 v2, v2, v5, s61
	v_and_b32_e32 v3, 0xffff0000, v3
	v_and_b32_e32 v2, 0xffff0000, v2
	v_or_b32_sdwa v1, v3, v1 dst_sel:DWORD dst_unused:UNUSED_PAD src0_sel:DWORD src1_sel:WORD_1
	v_or_b32_sdwa v0, v2, v0 dst_sel:DWORD dst_unused:UNUSED_PAD src0_sel:DWORD src1_sel:WORD_1
	global_store_dwordx2 v[36:37], v[0:1], off offset:96
	v_mov_b32_e32 v0, v12
	v_mov_b32_e32 v1, v14
	v_pk_mul_f32 v[0:1], v[0:1], v[32:33] op_sel_hi:[1,0]
	v_mov_b32_e32 v14, v13
	v_pk_mul_f32 v[2:3], v[14:15], v[32:33] op_sel_hi:[1,0]
	v_and_b32_sdwa v4, v1, v155 dst_sel:DWORD dst_unused:UNUSED_PAD src0_sel:WORD_1 src1_sel:DWORD
	v_and_b32_sdwa v5, v0, v155 dst_sel:DWORD dst_unused:UNUSED_PAD src0_sel:WORD_1 src1_sel:DWORD
	v_add3_u32 v0, v0, v5, s61
	v_add3_u32 v1, v1, v4, s61
	v_and_b32_sdwa v4, v3, v155 dst_sel:DWORD dst_unused:UNUSED_PAD src0_sel:WORD_1 src1_sel:DWORD
	v_and_b32_sdwa v5, v2, v155 dst_sel:DWORD dst_unused:UNUSED_PAD src0_sel:WORD_1 src1_sel:DWORD
	v_add3_u32 v3, v3, v4, s61
	v_add3_u32 v2, v2, v5, s61
	v_and_b32_e32 v3, 0xffff0000, v3
	v_and_b32_e32 v2, 0xffff0000, v2
	v_or_b32_sdwa v1, v3, v1 dst_sel:DWORD dst_unused:UNUSED_PAD src0_sel:DWORD src1_sel:WORD_1
	v_or_b32_sdwa v0, v2, v0 dst_sel:DWORD dst_unused:UNUSED_PAD src0_sel:DWORD src1_sel:WORD_1
	global_store_dwordx2 v[36:37], v[0:1], off offset:112
	s_branch .LBB0_1562
